# prologue weight transposes: 32 loads in flight per wave (4 groups issued before the first LDS write) + K-norm loop second load group hoisted
# baseline (speedup 1.0000x reference)
; #define LAS __attribute__((address_space(3)))
; #define LDS_WAIT() asm volatile("s_waitcnt lgkmcnt(0)" ::: "memory")
; __device__ __forceinline__ unsigned pk2(float lo, float hi) { return f2bf(lo) | (f2bf(hi) << 16); }
; __device__ __forceinline__ void transpose_item(const float* W, int K, int N, bf16* WT, int k0, int n0, int drow0, LAS float* scr, int lane) {
;     ...
;     for (int i = 0; i < 32; ++i) { const int kk = 2 * i + (lane >> 5); scr[kk * 33 + (lane & 31)] = __builtin_nontemporal_load(W + (size_t)(k0 + kk) * N + n0 + (lane & 31)); }
;     LDS_WAIT(); asm volatile("" ::: "memory");
;     const int c = lane & 7;
; #pragma unroll
;     for (int j = 0; j < 4; ++j) { const int n = (lane >> 3) + 8 * j; const LAS float* s = scr + (8 * c) * 33 + n;
;         v4u o; o.x = pk2(s[0 * 33], s[1 * 33]); o.y = pk2(s[2 * 33], s[3 * 33]); o.z = pk2(s[4 * 33], s[5 * 33]); o.w = pk2(s[6 * 33], s[7 * 33]);
;         __builtin_nontemporal_store(o, (v4u*)(WT + (size_t)(drow0 + n) * K + k0 + 8 * c)); }
.LBB0_10:
	v_lshl_add_u64 v[42:43], v[22:23], 0, s[10:11]
	v_lshl_add_u64 v[44:45], v[20:21], 0, s[10:11]
	v_lshl_add_u64 v[46:47], v[18:19], 0, s[10:11]
	v_lshl_add_u64 v[48:49], v[16:17], 0, s[10:11]
	v_lshl_add_u64 v[50:51], v[14:15], 0, s[10:11]
	v_lshl_add_u64 v[52:53], v[12:13], 0, s[10:11]
	v_lshl_add_u64 v[54:55], v[10:11], 0, s[10:11]
	v_lshl_add_u64 v[56:57], v[8:9], 0, s[10:11]
	global_load_dword v41, v[42:43], off nt
	global_load_dword v58, v[44:45], off nt
	global_load_dword v59, v[46:47], off nt
	global_load_dword v60, v[48:49], off nt
	global_load_dword v61, v[50:51], off nt
	global_load_dword v62, v[52:53], off nt
	global_load_dword v63, v[54:55], off nt
	global_load_dword v64, v[56:57], off nt
	s_add_u32 s10, s10, 0x30000
	s_addc_u32 s11, s11, 0
	v_lshl_add_u64 v[42:43], v[22:23], 0, s[10:11]
	v_lshl_add_u64 v[44:45], v[20:21], 0, s[10:11]
	v_lshl_add_u64 v[46:47], v[18:19], 0, s[10:11]
	v_lshl_add_u64 v[48:49], v[16:17], 0, s[10:11]
	v_lshl_add_u64 v[50:51], v[14:15], 0, s[10:11]
	v_lshl_add_u64 v[52:53], v[12:13], 0, s[10:11]
	v_lshl_add_u64 v[54:55], v[10:11], 0, s[10:11]
	v_lshl_add_u64 v[56:57], v[8:9], 0, s[10:11]
	global_load_dword v65, v[42:43], off nt
	global_load_dword v66, v[44:45], off nt
	global_load_dword v67, v[46:47], off nt
	global_load_dword v68, v[48:49], off nt
	global_load_dword v69, v[50:51], off nt
	global_load_dword v70, v[52:53], off nt
	global_load_dword v71, v[54:55], off nt
	global_load_dword v72, v[56:57], off nt
	s_add_u32 s10, s10, 0x30000
	s_addc_u32 s11, s11, 0
	v_lshl_add_u64 v[42:43], v[22:23], 0, s[10:11]
	v_lshl_add_u64 v[44:45], v[20:21], 0, s[10:11]
	v_lshl_add_u64 v[46:47], v[18:19], 0, s[10:11]
	v_lshl_add_u64 v[48:49], v[16:17], 0, s[10:11]
	v_lshl_add_u64 v[50:51], v[14:15], 0, s[10:11]
	v_lshl_add_u64 v[52:53], v[12:13], 0, s[10:11]
	v_lshl_add_u64 v[54:55], v[10:11], 0, s[10:11]
	v_lshl_add_u64 v[56:57], v[8:9], 0, s[10:11]
	global_load_dword v73, v[42:43], off nt
	global_load_dword v74, v[44:45], off nt
	global_load_dword v75, v[46:47], off nt
	global_load_dword v76, v[48:49], off nt
	global_load_dword v77, v[50:51], off nt
	global_load_dword v78, v[52:53], off nt
	global_load_dword v79, v[54:55], off nt
	global_load_dword v80, v[56:57], off nt
	s_add_u32 s10, s10, 0x30000
	s_addc_u32 s11, s11, 0
	v_lshl_add_u64 v[42:43], v[22:23], 0, s[10:11]
	v_lshl_add_u64 v[44:45], v[20:21], 0, s[10:11]
	v_lshl_add_u64 v[46:47], v[18:19], 0, s[10:11]
	v_lshl_add_u64 v[48:49], v[16:17], 0, s[10:11]
	v_lshl_add_u64 v[50:51], v[14:15], 0, s[10:11]
	v_lshl_add_u64 v[52:53], v[12:13], 0, s[10:11]
	v_lshl_add_u64 v[54:55], v[10:11], 0, s[10:11]
	v_lshl_add_u64 v[56:57], v[8:9], 0, s[10:11]
	global_load_dword v81, v[42:43], off nt
	global_load_dword v82, v[44:45], off nt
	global_load_dword v83, v[46:47], off nt
	global_load_dword v84, v[48:49], off nt
	global_load_dword v85, v[50:51], off nt
	global_load_dword v86, v[52:53], off nt
	global_load_dword v87, v[54:55], off nt
	global_load_dword v88, v[56:57], off nt
	s_add_u32 s10, s10, 0x30000
	s_addc_u32 s11, s11, 0
	v_add_u32_e32 v89, 0x400, v40
	s_waitcnt vmcnt(30)
	ds_write2_b32 v40, v41, v58 offset1:66
	s_waitcnt vmcnt(28)
	ds_write2_b32 v40, v59, v60 offset0:132 offset1:198
	s_waitcnt vmcnt(26)
	ds_write2_b32 v89, v61, v62 offset0:8 offset1:74
	s_waitcnt vmcnt(24)
	ds_write2_b32 v89, v63, v64 offset0:140 offset1:206
	v_add_u32_e32 v40, 0x840, v40
	v_add_u32_e32 v89, 0x400, v40
	s_waitcnt vmcnt(22)
	ds_write2_b32 v40, v65, v66 offset1:66
	s_waitcnt vmcnt(20)
	ds_write2_b32 v40, v67, v68 offset0:132 offset1:198
	s_waitcnt vmcnt(18)
	ds_write2_b32 v89, v69, v70 offset0:8 offset1:74
	s_waitcnt vmcnt(16)
	ds_write2_b32 v89, v71, v72 offset0:140 offset1:206
	v_add_u32_e32 v40, 0x840, v40
	v_add_u32_e32 v89, 0x400, v40
	s_waitcnt vmcnt(14)
	ds_write2_b32 v40, v73, v74 offset1:66
	s_waitcnt vmcnt(12)
	ds_write2_b32 v40, v75, v76 offset0:132 offset1:198
	s_waitcnt vmcnt(10)
	ds_write2_b32 v89, v77, v78 offset0:8 offset1:74
	s_waitcnt vmcnt(8)
	ds_write2_b32 v89, v79, v80 offset0:140 offset1:206
	v_add_u32_e32 v40, 0x840, v40
	v_add_u32_e32 v89, 0x400, v40
	s_waitcnt vmcnt(6)
	ds_write2_b32 v40, v81, v82 offset1:66
	s_waitcnt vmcnt(4)
	ds_write2_b32 v40, v83, v84 offset0:132 offset1:198
	s_waitcnt vmcnt(2)
	ds_write2_b32 v89, v85, v86 offset0:8 offset1:74
	s_waitcnt vmcnt(0)
	ds_write2_b32 v89, v87, v88 offset0:140 offset1:206
	v_add_u32_e32 v40, 0x840, v40
	s_waitcnt lgkmcnt(0)
	ds_read2_b32 v[12:13], v28 offset1:8
	ds_read2_b32 v[16:17], v28 offset0:33 offset1:41
	ds_read2_b32 v[18:19], v28 offset0:66 offset1:74
	ds_read2_b32 v[20:21], v28 offset0:99 offset1:107
	ds_read2_b32 v[22:23], v28 offset0:132 offset1:140
	s_waitcnt lgkmcnt(4)
	v_bfe_u32 v8, v12, 16, 1
	v_add3_u32 v8, v12, v8, s15
	s_waitcnt lgkmcnt(3)
; #define LAS __attribute__((address_space(3)))
; __device__ __forceinline__ unsigned pk2(float lo, float hi) { return f2bf(lo) | (f2bf(hi) << 16); }
; __device__ __forceinline__ void transpose_item(const float* W, int K, int N, bf16* WT, int k0, int n0, int drow0, LAS float* scr, int lane) {
;     ...
;     const int c = lane & 7;
; #pragma unroll
;     for (int j = 0; j < 4; ++j) { const int n = (lane >> 3) + 8 * j; const LAS float* s = scr + (8 * c) * 33 + n;
;         v4u o; o.x = pk2(s[0 * 33], s[1 * 33]); o.y = pk2(s[2 * 33], s[3 * 33]); o.z = pk2(s[4 * 33], s[5 * 33]); o.w = pk2(s[6 * 33], s[7 * 33]);
;         __builtin_nontemporal_store(o, (v4u*)(WT + (size_t)(drow0 + n) * K + k0 + 8 * c)); }
; template <bool GU>
; __device__ __forceinline__ void transpose_family(const float* W, int nmat, int K, int N, bf16* WT, size_t dstride, LAS float* scr, int gw, int NGW, int lane) {
;     ...
;     for (int it = gw; it < total; it += NGW) {
	v_bfe_u32 v9, v16, 16, 1
	v_lshrrev_b32_e32 v8, 16, v8
	v_add3_u32 v9, v16, v9, s15
	ds_read2_b32 v[40:41], v28 offset0:165 offset1:173
	v_and_or_b32 v8, v9, s22, v8
	s_waitcnt lgkmcnt(3)
	v_bfe_u32 v9, v18, 16, 1
	v_add3_u32 v9, v18, v9, s15
	s_waitcnt lgkmcnt(2)
	v_bfe_u32 v10, v20, 16, 1
	ds_read2_b32 v[42:43], v28 offset0:198 offset1:206
	v_lshrrev_b32_e32 v9, 16, v9
	v_add3_u32 v10, v20, v10, s15
	ds_read2_b32 v[44:45], v28 offset0:231 offset1:239
	s_mul_i32 s10, s26, 0xc00000
	v_and_or_b32 v9, v10, s22, v9
	s_waitcnt lgkmcnt(3)
	v_bfe_u32 v10, v22, 16, 1
	s_mul_hi_i32 s7, s26, 0xc00000
	s_add_u32 s10, s12, s10
	v_add3_u32 v10, v22, v10, s15
	s_waitcnt lgkmcnt(2)
	v_bfe_u32 v11, v40, 16, 1
	s_addc_u32 s7, s13, s7
	s_lshl_b64 s[8:9], s[8:9], 1
	v_lshrrev_b32_e32 v10, 16, v10
	v_add3_u32 v11, v40, v11, s15
	s_add_u32 s8, s10, s8
	v_and_or_b32 v10, v11, s22, v10
	s_waitcnt lgkmcnt(1)
	v_bfe_u32 v11, v42, 16, 1
	v_or_b32_e32 v46, s6, v24
	s_addc_u32 s9, s7, s9
	v_add3_u32 v11, v42, v11, s15
	s_waitcnt lgkmcnt(0)
	v_bfe_u32 v12, v44, 16, 1
	v_ashrrev_i32_e32 v47, 31, v46
	v_lshl_add_u64 v[14:15], s[8:9], 0, v[4:5]
	v_lshrrev_b32_e32 v11, 16, v11
	v_add3_u32 v12, v44, v12, s15
	v_lshlrev_b64 v[46:47], 12, v[46:47]
	v_and_or_b32 v11, v12, s22, v11
	v_lshl_add_u64 v[46:47], v[14:15], 0, v[46:47]
	global_store_dwordx4 v[46:47], v[8:11], off nt
	v_bfe_u32 v12, v45, 16, 1
	v_add3_u32 v12, v45, v12, s15
	v_bfe_u32 v8, v13, 16, 1
	v_add3_u32 v8, v13, v8, s15
	v_bfe_u32 v9, v17, 16, 1
	v_lshrrev_b32_e32 v8, 16, v8
	v_add3_u32 v9, v17, v9, s15
	v_and_or_b32 v8, v9, s22, v8
	v_bfe_u32 v9, v19, 16, 1
	v_add3_u32 v9, v19, v9, s15
	v_bfe_u32 v10, v21, 16, 1
	v_lshrrev_b32_e32 v9, 16, v9
	v_add3_u32 v10, v21, v10, s15
	v_and_or_b32 v9, v10, s22, v9
	v_bfe_u32 v10, v23, 16, 1
	v_add3_u32 v10, v23, v10, s15
	v_bfe_u32 v11, v41, 16, 1
	v_lshrrev_b32_e32 v10, 16, v10
	v_add3_u32 v11, v41, v11, s15
	v_and_or_b32 v10, v11, s22, v10
	v_bfe_u32 v11, v43, 16, 1
	v_add3_u32 v11, v43, v11, s15
	v_lshrrev_b32_e32 v11, 16, v11
	v_and_or_b32 v11, v12, s22, v11
	v_or_b32_e32 v12, s6, v29
	v_ashrrev_i32_e32 v13, 31, v12
	v_lshlrev_b64 v[12:13], 12, v[12:13]
	ds_read2_b32 v[16:17], v28 offset0:16 offset1:24
	v_lshl_add_u64 v[12:13], v[14:15], 0, v[12:13]
	global_store_dwordx4 v[12:13], v[8:11], off nt
	ds_read2_b32 v[12:13], v28 offset0:49 offset1:57
	ds_read2_b32 v[18:19], v28 offset0:82 offset1:90
	ds_read2_b32 v[20:21], v28 offset0:115 offset1:123
	s_waitcnt lgkmcnt(3)
	v_bfe_u32 v8, v16, 16, 1
	v_add3_u32 v8, v16, v8, s15
	s_waitcnt lgkmcnt(2)
	v_bfe_u32 v9, v12, 16, 1
	ds_read2_b32 v[22:23], v28 offset0:148 offset1:156
	v_lshrrev_b32_e32 v8, 16, v8
	v_add3_u32 v9, v12, v9, s15
	ds_read2_b32 v[40:41], v28 offset0:181 offset1:189
	v_and_or_b32 v8, v9, s22, v8
	s_waitcnt lgkmcnt(3)
	v_bfe_u32 v9, v18, 16, 1
	v_add3_u32 v9, v18, v9, s15
	s_waitcnt lgkmcnt(2)
	v_bfe_u32 v10, v20, 16, 1
	ds_read2_b32 v[42:43], v28 offset0:214 offset1:222
	v_lshrrev_b32_e32 v9, 16, v9
	v_add3_u32 v10, v20, v10, s15
	ds_read2_b32 v[44:45], v28 offset0:247 offset1:255
	v_and_or_b32 v9, v10, s22, v9
	s_waitcnt lgkmcnt(3)
	v_bfe_u32 v10, v22, 16, 1
	v_add3_u32 v10, v22, v10, s15
	s_waitcnt lgkmcnt(2)
	v_bfe_u32 v11, v40, 16, 1
	v_lshrrev_b32_e32 v10, 16, v10
	v_add3_u32 v11, v40, v11, s15
	v_and_or_b32 v10, v11, s22, v10
	s_waitcnt lgkmcnt(1)
	v_bfe_u32 v11, v42, 16, 1
	v_or_b32_e32 v46, s6, v30
	v_add3_u32 v11, v42, v11, s15
	s_waitcnt lgkmcnt(0)
	v_bfe_u32 v12, v44, 16, 1
	v_ashrrev_i32_e32 v47, 31, v46
	v_lshrrev_b32_e32 v11, 16, v11
	v_add3_u32 v12, v44, v12, s15
	v_lshlrev_b64 v[46:47], 12, v[46:47]
	v_and_or_b32 v11, v12, s22, v11
	v_lshl_add_u64 v[46:47], v[14:15], 0, v[46:47]
	global_store_dwordx4 v[46:47], v[8:11], off nt
	v_bfe_u32 v12, v45, 16, 1
	v_add3_u32 v12, v45, v12, s15
	v_bfe_u32 v8, v17, 16, 1
	v_add3_u32 v8, v17, v8, s15
	v_bfe_u32 v9, v13, 16, 1
	v_lshrrev_b32_e32 v8, 16, v8
	v_add3_u32 v9, v13, v9, s15
	v_and_or_b32 v8, v9, s22, v8
	v_bfe_u32 v9, v19, 16, 1
	v_add3_u32 v9, v19, v9, s15
	v_bfe_u32 v10, v21, 16, 1
	v_lshrrev_b32_e32 v9, 16, v9
	v_add3_u32 v10, v21, v10, s15
	v_and_or_b32 v9, v10, s22, v9
	v_bfe_u32 v10, v23, 16, 1
	v_add3_u32 v10, v23, v10, s15
	v_bfe_u32 v11, v41, 16, 1
	v_lshrrev_b32_e32 v10, 16, v10
	v_add3_u32 v11, v41, v11, s15
	v_and_or_b32 v10, v11, s22, v10
	v_bfe_u32 v11, v43, 16, 1
	v_add3_u32 v11, v43, v11, s15
	v_lshrrev_b32_e32 v11, 16, v11
	v_and_or_b32 v11, v12, s22, v11
	v_or_b32_e32 v12, s6, v31
	v_ashrrev_i32_e32 v13, 31, v12
	v_lshlrev_b64 v[12:13], 12, v[12:13]
	v_lshl_add_u64 v[12:13], v[14:15], 0, v[12:13]
	global_store_dwordx4 v[12:13], v[8:11], off nt
	s_waitcnt lgkmcnt(0)
	s_add_i32 s23, s23, s62
	s_cmpk_lt_i32 s23, 0x1800
	s_cbranch_scc1 .LBB0_9

; #define LDS_WAIT() asm volatile("s_waitcnt lgkmcnt(0)" ::: "memory")
; __device__ __forceinline__ void transpose_item(const float* W, int K, int N, bf16* WT, int k0, int n0, int drow0, LAS float* scr, int lane) {
;     ...
;     for (int i = 0; i < 32; ++i) { const int kk = 2 * i + (lane >> 5); scr[kk * 33 + (lane & 31)] = __builtin_nontemporal_load(W + (size_t)(k0 + kk) * N + n0 + (lane & 31)); }
;     LDS_WAIT(); asm volatile("" ::: "memory");
.LBB0_15:
	v_lshl_add_u64 v[42:43], v[22:23], 0, s[30:31]
	v_lshl_add_u64 v[44:45], v[20:21], 0, s[30:31]
	v_lshl_add_u64 v[46:47], v[18:19], 0, s[30:31]
	v_lshl_add_u64 v[48:49], v[16:17], 0, s[30:31]
	v_lshl_add_u64 v[50:51], v[14:15], 0, s[30:31]
	v_lshl_add_u64 v[52:53], v[12:13], 0, s[30:31]
	v_lshl_add_u64 v[54:55], v[10:11], 0, s[30:31]
	v_lshl_add_u64 v[56:57], v[8:9], 0, s[30:31]
	global_load_dword v41, v[42:43], off nt
	global_load_dword v58, v[44:45], off nt
	global_load_dword v59, v[46:47], off nt
	global_load_dword v60, v[48:49], off nt
	global_load_dword v61, v[50:51], off nt
	global_load_dword v62, v[52:53], off nt
	global_load_dword v63, v[54:55], off nt
	global_load_dword v64, v[56:57], off nt
	s_add_u32 s30, s30, 0x20000
	s_addc_u32 s31, s31, 0
	v_lshl_add_u64 v[42:43], v[22:23], 0, s[30:31]
	v_lshl_add_u64 v[44:45], v[20:21], 0, s[30:31]
	v_lshl_add_u64 v[46:47], v[18:19], 0, s[30:31]
	v_lshl_add_u64 v[48:49], v[16:17], 0, s[30:31]
	v_lshl_add_u64 v[50:51], v[14:15], 0, s[30:31]
	v_lshl_add_u64 v[52:53], v[12:13], 0, s[30:31]
	v_lshl_add_u64 v[54:55], v[10:11], 0, s[30:31]
	v_lshl_add_u64 v[56:57], v[8:9], 0, s[30:31]
	global_load_dword v65, v[42:43], off nt
	global_load_dword v66, v[44:45], off nt
	global_load_dword v67, v[46:47], off nt
	global_load_dword v68, v[48:49], off nt
	global_load_dword v69, v[50:51], off nt
	global_load_dword v70, v[52:53], off nt
	global_load_dword v71, v[54:55], off nt
	global_load_dword v72, v[56:57], off nt
	s_add_u32 s30, s30, 0x20000
	s_addc_u32 s31, s31, 0
	v_lshl_add_u64 v[42:43], v[22:23], 0, s[30:31]
	v_lshl_add_u64 v[44:45], v[20:21], 0, s[30:31]
	v_lshl_add_u64 v[46:47], v[18:19], 0, s[30:31]
	v_lshl_add_u64 v[48:49], v[16:17], 0, s[30:31]
	v_lshl_add_u64 v[50:51], v[14:15], 0, s[30:31]
	v_lshl_add_u64 v[52:53], v[12:13], 0, s[30:31]
	v_lshl_add_u64 v[54:55], v[10:11], 0, s[30:31]
	v_lshl_add_u64 v[56:57], v[8:9], 0, s[30:31]
	global_load_dword v73, v[42:43], off nt
	global_load_dword v74, v[44:45], off nt
	global_load_dword v75, v[46:47], off nt
	global_load_dword v76, v[48:49], off nt
	global_load_dword v77, v[50:51], off nt
	global_load_dword v78, v[52:53], off nt
	global_load_dword v79, v[54:55], off nt
	global_load_dword v80, v[56:57], off nt
	s_add_u32 s30, s30, 0x20000
	s_addc_u32 s31, s31, 0
	v_lshl_add_u64 v[42:43], v[22:23], 0, s[30:31]
	v_lshl_add_u64 v[44:45], v[20:21], 0, s[30:31]
	v_lshl_add_u64 v[46:47], v[18:19], 0, s[30:31]
	v_lshl_add_u64 v[48:49], v[16:17], 0, s[30:31]
	v_lshl_add_u64 v[50:51], v[14:15], 0, s[30:31]
	v_lshl_add_u64 v[52:53], v[12:13], 0, s[30:31]
	v_lshl_add_u64 v[54:55], v[10:11], 0, s[30:31]
	v_lshl_add_u64 v[56:57], v[8:9], 0, s[30:31]
	global_load_dword v81, v[42:43], off nt
	global_load_dword v82, v[44:45], off nt
	global_load_dword v83, v[46:47], off nt
	global_load_dword v84, v[48:49], off nt
	global_load_dword v85, v[50:51], off nt
	global_load_dword v86, v[52:53], off nt
	global_load_dword v87, v[54:55], off nt
	global_load_dword v88, v[56:57], off nt
	s_add_u32 s30, s30, 0x20000
	s_addc_u32 s31, s31, 0
	v_add_u32_e32 v89, 0x400, v40
	s_waitcnt vmcnt(30)
	ds_write2_b32 v40, v41, v58 offset1:66
	s_waitcnt vmcnt(28)
	ds_write2_b32 v40, v59, v60 offset0:132 offset1:198
	s_waitcnt vmcnt(26)
	ds_write2_b32 v89, v61, v62 offset0:8 offset1:74
	s_waitcnt vmcnt(24)
	ds_write2_b32 v89, v63, v64 offset0:140 offset1:206
	v_add_u32_e32 v40, 0x840, v40
	v_add_u32_e32 v89, 0x400, v40
	s_waitcnt vmcnt(22)
	ds_write2_b32 v40, v65, v66 offset1:66
	s_waitcnt vmcnt(20)
	ds_write2_b32 v40, v67, v68 offset0:132 offset1:198
	s_waitcnt vmcnt(18)
	ds_write2_b32 v89, v69, v70 offset0:8 offset1:74
	s_waitcnt vmcnt(16)
	ds_write2_b32 v89, v71, v72 offset0:140 offset1:206
	v_add_u32_e32 v40, 0x840, v40
	v_add_u32_e32 v89, 0x400, v40
	s_waitcnt vmcnt(14)
	ds_write2_b32 v40, v73, v74 offset1:66
	s_waitcnt vmcnt(12)
	ds_write2_b32 v40, v75, v76 offset0:132 offset1:198
	s_waitcnt vmcnt(10)
	ds_write2_b32 v89, v77, v78 offset0:8 offset1:74
	s_waitcnt vmcnt(8)
	ds_write2_b32 v89, v79, v80 offset0:140 offset1:206
	v_add_u32_e32 v40, 0x840, v40
	v_add_u32_e32 v89, 0x400, v40
	s_waitcnt vmcnt(6)
	ds_write2_b32 v40, v81, v82 offset1:66
	s_waitcnt vmcnt(4)
	ds_write2_b32 v40, v83, v84 offset0:132 offset1:198
	s_waitcnt vmcnt(2)
	ds_write2_b32 v89, v85, v86 offset0:8 offset1:74
	s_waitcnt vmcnt(0)
	ds_write2_b32 v89, v87, v88 offset0:140 offset1:206
	v_add_u32_e32 v40, 0x840, v40
	s_waitcnt lgkmcnt(0)
	ds_read2_b32 v[12:13], v28 offset1:8
	ds_read2_b32 v[16:17], v28 offset0:33 offset1:41
	ds_read2_b32 v[18:19], v28 offset0:66 offset1:74
	ds_read2_b32 v[20:21], v28 offset0:99 offset1:107
	ds_read2_b32 v[22:23], v28 offset0:132 offset1:140
	s_waitcnt lgkmcnt(4)
	v_bfe_u32 v8, v12, 16, 1
	v_add3_u32 v8, v12, v8, s37
	s_waitcnt lgkmcnt(3)
; #define LAS __attribute__((address_space(3)))
; #define LDS_WAIT() asm volatile("s_waitcnt lgkmcnt(0)" ::: "memory")
; __device__ __forceinline__ unsigned pk2(float lo, float hi) { return f2bf(lo) | (f2bf(hi) << 16); }
; __device__ __forceinline__ void transpose_item(const float* W, int K, int N, bf16* WT, int k0, int n0, int drow0, LAS float* scr, int lane) {
;     ...
;     const int c = lane & 7;
; #pragma unroll
;     for (int j = 0; j < 4; ++j) { const int n = (lane >> 3) + 8 * j; const LAS float* s = scr + (8 * c) * 33 + n;
;         v4u o; o.x = pk2(s[0 * 33], s[1 * 33]); o.y = pk2(s[2 * 33], s[3 * 33]); o.z = pk2(s[4 * 33], s[5 * 33]); o.w = pk2(s[6 * 33], s[7 * 33]);
;         __builtin_nontemporal_store(o, (v4u*)(WT + (size_t)(drow0 + n) * K + k0 + 8 * c)); }
;     LDS_WAIT(); asm volatile("" ::: "memory");
; template <bool GU>
; __device__ __forceinline__ void transpose_family(const float* W, int nmat, int K, int N, bf16* WT, size_t dstride, LAS float* scr, int gw, int NGW, int lane) {
;     ...
;     for (int it = gw; it < total; it += NGW) {
;         const int mi = it / per, r = it % per, kb = r / nblk, nb = r % nblk, n0 = nb * 32;
;         int drow0 = n0;
;         if (GU) { const int j = n0 < DFF ? n0 : n0 - DFF; drow0 = (j >> 7) * 256 + (n0 < DFF ? 0 : 128) + (j & 127); }
;         transpose_item(W + (size_t)mi * K * N, K, N, WT + (size_t)mi * dstride, kb * 64, n0, drow0, scr, lane);
	v_bfe_u32 v9, v16, 16, 1
	v_lshrrev_b32_e32 v8, 16, v8
	v_add3_u32 v9, v16, v9, s37
	ds_read2_b32 v[40:41], v28 offset0:165 offset1:173
	v_and_or_b32 v8, v9, s38, v8
	s_waitcnt lgkmcnt(3)
	v_bfe_u32 v9, v18, 16, 1
	v_add3_u32 v9, v18, v9, s37
	s_waitcnt lgkmcnt(2)
	v_bfe_u32 v10, v20, 16, 1
	ds_read2_b32 v[42:43], v28 offset0:198 offset1:206
	v_lshrrev_b32_e32 v9, 16, v9
	v_add3_u32 v10, v20, v10, s37
	ds_read2_b32 v[44:45], v28 offset0:231 offset1:239
	s_lshl_b64 s[12:13], s[12:13], 23
	v_and_or_b32 v9, v10, s38, v9
	s_waitcnt lgkmcnt(3)
	v_bfe_u32 v10, v22, 16, 1
	s_add_u32 s7, s35, s12
	v_add3_u32 v10, v22, v10, s37
	s_waitcnt lgkmcnt(2)
	v_bfe_u32 v11, v40, 16, 1
	s_addc_u32 s30, s36, s13
	s_lshl_b64 s[12:13], s[28:29], 1
	v_lshrrev_b32_e32 v10, 16, v10
	v_add3_u32 v11, v40, v11, s37
	s_add_u32 s12, s7, s12
	v_and_or_b32 v10, v11, s38, v10
	s_waitcnt lgkmcnt(1)
	v_bfe_u32 v11, v42, 16, 1
	v_or_b32_e32 v46, s6, v24
	s_addc_u32 s13, s30, s13
	v_add3_u32 v11, v42, v11, s37
	s_waitcnt lgkmcnt(0)
	v_bfe_u32 v12, v44, 16, 1
	v_ashrrev_i32_e32 v47, 31, v46
	v_lshl_add_u64 v[14:15], s[12:13], 0, v[4:5]
	v_lshrrev_b32_e32 v11, 16, v11
	v_add3_u32 v12, v44, v12, s37
	v_lshlrev_b64 v[46:47], 12, v[46:47]
	v_and_or_b32 v11, v12, s38, v11
	v_lshl_add_u64 v[46:47], v[14:15], 0, v[46:47]
	global_store_dwordx4 v[46:47], v[8:11], off nt
	v_bfe_u32 v12, v45, 16, 1
	v_add3_u32 v12, v45, v12, s37
	v_bfe_u32 v8, v13, 16, 1
	v_add3_u32 v8, v13, v8, s37
	v_bfe_u32 v9, v17, 16, 1
	v_lshrrev_b32_e32 v8, 16, v8
	v_add3_u32 v9, v17, v9, s37
	v_and_or_b32 v8, v9, s38, v8
	v_bfe_u32 v9, v19, 16, 1
	v_add3_u32 v9, v19, v9, s37
	v_bfe_u32 v10, v21, 16, 1
	v_lshrrev_b32_e32 v9, 16, v9
	v_add3_u32 v10, v21, v10, s37
	v_and_or_b32 v9, v10, s38, v9
	v_bfe_u32 v10, v23, 16, 1
	v_add3_u32 v10, v23, v10, s37
	v_bfe_u32 v11, v41, 16, 1
	v_lshrrev_b32_e32 v10, 16, v10
	v_add3_u32 v11, v41, v11, s37
	v_and_or_b32 v10, v11, s38, v10
	v_bfe_u32 v11, v43, 16, 1
	v_add3_u32 v11, v43, v11, s37
	v_lshrrev_b32_e32 v11, 16, v11
	v_and_or_b32 v11, v12, s38, v11
	v_or_b32_e32 v12, s6, v29
	v_ashrrev_i32_e32 v13, 31, v12
	v_lshlrev_b64 v[12:13], 12, v[12:13]
	ds_read2_b32 v[16:17], v28 offset0:16 offset1:24
	v_lshl_add_u64 v[12:13], v[14:15], 0, v[12:13]
	global_store_dwordx4 v[12:13], v[8:11], off nt
	ds_read2_b32 v[12:13], v28 offset0:49 offset1:57
	ds_read2_b32 v[18:19], v28 offset0:82 offset1:90
	ds_read2_b32 v[20:21], v28 offset0:115 offset1:123
	s_waitcnt lgkmcnt(3)
	v_bfe_u32 v8, v16, 16, 1
	v_add3_u32 v8, v16, v8, s37
	s_waitcnt lgkmcnt(2)
	v_bfe_u32 v9, v12, 16, 1
	ds_read2_b32 v[22:23], v28 offset0:148 offset1:156
	v_lshrrev_b32_e32 v8, 16, v8
	v_add3_u32 v9, v12, v9, s37
	ds_read2_b32 v[40:41], v28 offset0:181 offset1:189
	v_and_or_b32 v8, v9, s38, v8
	s_waitcnt lgkmcnt(3)
	v_bfe_u32 v9, v18, 16, 1
	v_add3_u32 v9, v18, v9, s37
	s_waitcnt lgkmcnt(2)
	v_bfe_u32 v10, v20, 16, 1
	ds_read2_b32 v[42:43], v28 offset0:214 offset1:222
	v_lshrrev_b32_e32 v9, 16, v9
	v_add3_u32 v10, v20, v10, s37
	ds_read2_b32 v[44:45], v28 offset0:247 offset1:255
	v_and_or_b32 v9, v10, s38, v9
	s_waitcnt lgkmcnt(3)
	v_bfe_u32 v10, v22, 16, 1
	v_add3_u32 v10, v22, v10, s37
	s_waitcnt lgkmcnt(2)
	v_bfe_u32 v11, v40, 16, 1
	v_lshrrev_b32_e32 v10, 16, v10
	v_add3_u32 v11, v40, v11, s37
	v_and_or_b32 v10, v11, s38, v10
	s_waitcnt lgkmcnt(1)
	v_bfe_u32 v11, v42, 16, 1
	v_or_b32_e32 v46, s6, v30
	v_add3_u32 v11, v42, v11, s37
	s_waitcnt lgkmcnt(0)
	v_bfe_u32 v12, v44, 16, 1
	v_ashrrev_i32_e32 v47, 31, v46
	v_lshrrev_b32_e32 v11, 16, v11
	v_add3_u32 v12, v44, v12, s37
	v_lshlrev_b64 v[46:47], 12, v[46:47]
	v_and_or_b32 v11, v12, s38, v11
	v_lshl_add_u64 v[46:47], v[14:15], 0, v[46:47]
	global_store_dwordx4 v[46:47], v[8:11], off nt
	v_bfe_u32 v12, v45, 16, 1
	v_add3_u32 v12, v45, v12, s37
	v_bfe_u32 v8, v17, 16, 1
	v_add3_u32 v8, v17, v8, s37
	v_bfe_u32 v9, v13, 16, 1
	v_lshrrev_b32_e32 v8, 16, v8
	v_add3_u32 v9, v13, v9, s37
	v_and_or_b32 v8, v9, s38, v8
	v_bfe_u32 v9, v19, 16, 1
	v_add3_u32 v9, v19, v9, s37
	v_bfe_u32 v10, v21, 16, 1
	v_lshrrev_b32_e32 v9, 16, v9
	v_add3_u32 v10, v21, v10, s37
	v_and_or_b32 v9, v10, s38, v9
	v_bfe_u32 v10, v23, 16, 1
	v_add3_u32 v10, v23, v10, s37
	v_bfe_u32 v11, v41, 16, 1
	v_lshrrev_b32_e32 v10, 16, v10
	v_add3_u32 v11, v41, v11, s37
	v_and_or_b32 v10, v11, s38, v10
	v_bfe_u32 v11, v43, 16, 1
	v_add3_u32 v11, v43, v11, s37
	v_lshrrev_b32_e32 v11, 16, v11
	v_and_or_b32 v11, v12, s38, v11
	v_or_b32_e32 v12, s6, v31
	v_ashrrev_i32_e32 v13, 31, v12
	v_lshlrev_b64 v[12:13], 12, v[12:13]
	v_lshl_add_u64 v[12:13], v[14:15], 0, v[12:13]
	global_store_dwordx4 v[12:13], v[8:11], off nt
	s_waitcnt lgkmcnt(0)
	s_add_i32 s39, s39, s62
	s_cmpk_lt_i32 s39, 0x1000
	s_cbranch_scc1 .LBB0_14

; #define LAS __attribute__((address_space(3)))
; #define LDS_WAIT() asm volatile("s_waitcnt lgkmcnt(0)" ::: "memory")
; __device__ __forceinline__ void transpose_item(const float* W, int K, int N, bf16* WT, int k0, int n0, int drow0, LAS float* scr, int lane) {
;     ...
;     for (int i = 0; i < 32; ++i) { const int kk = 2 * i + (lane >> 5); scr[kk * 33 + (lane & 31)] = __builtin_nontemporal_load(W + (size_t)(k0 + kk) * N + n0 + (lane & 31)); }
;     LDS_WAIT(); asm volatile("" ::: "memory");
;     const int c = lane & 7;
; #pragma unroll
;     for (int j = 0; j < 4; ++j) { const int n = (lane >> 3) + 8 * j; const LAS float* s = scr + (8 * c) * 33 + n;
.LBB0_20:
	v_lshl_add_u64 v[42:43], v[22:23], 0, s[28:29]
	v_lshl_add_u64 v[44:45], v[20:21], 0, s[28:29]
	v_lshl_add_u64 v[46:47], v[18:19], 0, s[28:29]
	v_lshl_add_u64 v[48:49], v[16:17], 0, s[28:29]
	v_lshl_add_u64 v[50:51], v[14:15], 0, s[28:29]
	v_lshl_add_u64 v[52:53], v[12:13], 0, s[28:29]
	v_lshl_add_u64 v[54:55], v[10:11], 0, s[28:29]
	v_lshl_add_u64 v[56:57], v[8:9], 0, s[28:29]
	global_load_dword v41, v[42:43], off nt
	global_load_dword v58, v[44:45], off nt
	global_load_dword v59, v[46:47], off nt
	global_load_dword v60, v[48:49], off nt
	global_load_dword v61, v[50:51], off nt
	global_load_dword v62, v[52:53], off nt
	global_load_dword v63, v[54:55], off nt
	global_load_dword v64, v[56:57], off nt
	s_add_u32 s28, s28, 0x60800
	s_addc_u32 s29, s29, 0
	v_lshl_add_u64 v[42:43], v[22:23], 0, s[28:29]
	v_lshl_add_u64 v[44:45], v[20:21], 0, s[28:29]
	v_lshl_add_u64 v[46:47], v[18:19], 0, s[28:29]
	v_lshl_add_u64 v[48:49], v[16:17], 0, s[28:29]
	v_lshl_add_u64 v[50:51], v[14:15], 0, s[28:29]
	v_lshl_add_u64 v[52:53], v[12:13], 0, s[28:29]
	v_lshl_add_u64 v[54:55], v[10:11], 0, s[28:29]
	v_lshl_add_u64 v[56:57], v[8:9], 0, s[28:29]
	global_load_dword v65, v[42:43], off nt
	global_load_dword v66, v[44:45], off nt
	global_load_dword v67, v[46:47], off nt
	global_load_dword v68, v[48:49], off nt
	global_load_dword v69, v[50:51], off nt
	global_load_dword v70, v[52:53], off nt
	global_load_dword v71, v[54:55], off nt
	global_load_dword v72, v[56:57], off nt
	s_add_u32 s28, s28, 0x60800
	s_addc_u32 s29, s29, 0
	v_lshl_add_u64 v[42:43], v[22:23], 0, s[28:29]
	v_lshl_add_u64 v[44:45], v[20:21], 0, s[28:29]
	v_lshl_add_u64 v[46:47], v[18:19], 0, s[28:29]
	v_lshl_add_u64 v[48:49], v[16:17], 0, s[28:29]
	v_lshl_add_u64 v[50:51], v[14:15], 0, s[28:29]
	v_lshl_add_u64 v[52:53], v[12:13], 0, s[28:29]
	v_lshl_add_u64 v[54:55], v[10:11], 0, s[28:29]
	v_lshl_add_u64 v[56:57], v[8:9], 0, s[28:29]
	global_load_dword v73, v[42:43], off nt
	global_load_dword v74, v[44:45], off nt
	global_load_dword v75, v[46:47], off nt
	global_load_dword v76, v[48:49], off nt
	global_load_dword v77, v[50:51], off nt
	global_load_dword v78, v[52:53], off nt
	global_load_dword v79, v[54:55], off nt
	global_load_dword v80, v[56:57], off nt
	s_add_u32 s28, s28, 0x60800
	s_addc_u32 s29, s29, 0
	v_lshl_add_u64 v[42:43], v[22:23], 0, s[28:29]
	v_lshl_add_u64 v[44:45], v[20:21], 0, s[28:29]
	v_lshl_add_u64 v[46:47], v[18:19], 0, s[28:29]
	v_lshl_add_u64 v[48:49], v[16:17], 0, s[28:29]
	v_lshl_add_u64 v[50:51], v[14:15], 0, s[28:29]
	v_lshl_add_u64 v[52:53], v[12:13], 0, s[28:29]
	v_lshl_add_u64 v[54:55], v[10:11], 0, s[28:29]
	v_lshl_add_u64 v[56:57], v[8:9], 0, s[28:29]
	global_load_dword v81, v[42:43], off nt
	global_load_dword v82, v[44:45], off nt
	global_load_dword v83, v[46:47], off nt
	global_load_dword v84, v[48:49], off nt
	global_load_dword v85, v[50:51], off nt
	global_load_dword v86, v[52:53], off nt
	global_load_dword v87, v[54:55], off nt
	global_load_dword v88, v[56:57], off nt
	s_add_u32 s28, s28, 0x60800
	s_addc_u32 s29, s29, 0
	v_add_u32_e32 v89, 0x400, v40
	s_waitcnt vmcnt(30)
	ds_write2_b32 v40, v41, v58 offset1:66
	s_waitcnt vmcnt(28)
	ds_write2_b32 v40, v59, v60 offset0:132 offset1:198
	s_waitcnt vmcnt(26)
	ds_write2_b32 v89, v61, v62 offset0:8 offset1:74
	s_waitcnt vmcnt(24)
	ds_write2_b32 v89, v63, v64 offset0:140 offset1:206
	v_add_u32_e32 v40, 0x840, v40
	v_add_u32_e32 v89, 0x400, v40
	s_waitcnt vmcnt(22)
	ds_write2_b32 v40, v65, v66 offset1:66
	s_waitcnt vmcnt(20)
	ds_write2_b32 v40, v67, v68 offset0:132 offset1:198
	s_waitcnt vmcnt(18)
	ds_write2_b32 v89, v69, v70 offset0:8 offset1:74
	s_waitcnt vmcnt(16)
	ds_write2_b32 v89, v71, v72 offset0:140 offset1:206
	v_add_u32_e32 v40, 0x840, v40
	v_add_u32_e32 v89, 0x400, v40
	s_waitcnt vmcnt(14)
	ds_write2_b32 v40, v73, v74 offset1:66
	s_waitcnt vmcnt(12)
	ds_write2_b32 v40, v75, v76 offset0:132 offset1:198
	s_waitcnt vmcnt(10)
	ds_write2_b32 v89, v77, v78 offset0:8 offset1:74
	s_waitcnt vmcnt(8)
	ds_write2_b32 v89, v79, v80 offset0:140 offset1:206
	v_add_u32_e32 v40, 0x840, v40
	v_add_u32_e32 v89, 0x400, v40
	s_waitcnt vmcnt(6)
	ds_write2_b32 v40, v81, v82 offset1:66
	s_waitcnt vmcnt(4)
	ds_write2_b32 v40, v83, v84 offset0:132 offset1:198
	s_waitcnt vmcnt(2)
	ds_write2_b32 v89, v85, v86 offset0:8 offset1:74
	s_waitcnt vmcnt(0)
	ds_write2_b32 v89, v87, v88 offset0:140 offset1:206
	v_add_u32_e32 v40, 0x840, v40
	s_waitcnt lgkmcnt(0)
	ds_read2_b32 v[12:13], v28 offset1:8
	ds_read2_b32 v[16:17], v28 offset0:33 offset1:41
	ds_read2_b32 v[18:19], v28 offset0:66 offset1:74
	ds_read2_b32 v[20:21], v28 offset0:99 offset1:107
	ds_read2_b32 v[22:23], v28 offset0:132 offset1:140
	s_waitcnt lgkmcnt(4)
	v_bfe_u32 v8, v12, 16, 1
	v_add3_u32 v8, v12, v8, s31
	s_waitcnt lgkmcnt(3)
; #define LAS __attribute__((address_space(3)))
; #define LDS_WAIT() asm volatile("s_waitcnt lgkmcnt(0)" ::: "memory")
; __device__ __forceinline__ unsigned pk2(float lo, float hi) { return f2bf(lo) | (f2bf(hi) << 16); }
; __device__ __forceinline__ void transpose_item(const float* W, int K, int N, bf16* WT, int k0, int n0, int drow0, LAS float* scr, int lane) {
;     ...
;     const int c = lane & 7;
; #pragma unroll
;     for (int j = 0; j < 4; ++j) { const int n = (lane >> 3) + 8 * j; const LAS float* s = scr + (8 * c) * 33 + n;
;         v4u o; o.x = pk2(s[0 * 33], s[1 * 33]); o.y = pk2(s[2 * 33], s[3 * 33]); o.z = pk2(s[4 * 33], s[5 * 33]); o.w = pk2(s[6 * 33], s[7 * 33]);
;         __builtin_nontemporal_store(o, (v4u*)(WT + (size_t)(drow0 + n) * K + k0 + 8 * c)); }
;     LDS_WAIT(); asm volatile("" ::: "memory");
; }
; template <bool GU>
; __device__ __forceinline__ void transpose_family(const float* W, int nmat, int K, int N, bf16* WT, size_t dstride, LAS float* scr, int gw, int NGW, int lane) {
;     const int nblk = N / 32, per = (K / 64) * nblk, total = nmat * per;
;     for (int it = gw; it < total; it += NGW) {
;         const int mi = it / per, r = it % per, kb = r / nblk, nb = r % nblk, n0 = nb * 32;
;         int drow0 = n0;
;         if (GU) { const int j = n0 < DFF ? n0 : n0 - DFF; drow0 = (j >> 7) * 256 + (n0 < DFF ? 0 : 128) + (j & 127); }
;         transpose_item(W + (size_t)mi * K * N, K, N, WT + (size_t)mi * dstride, kb * 64, n0, drow0, scr, lane);
	v_bfe_u32 v9, v16, 16, 1
	v_lshrrev_b32_e32 v8, 16, v8
	v_add3_u32 v9, v16, v9, s31
	ds_read2_b32 v[40:41], v28 offset0:165 offset1:173
	v_and_or_b32 v8, v9, s35, v8
	s_waitcnt lgkmcnt(3)
	v_bfe_u32 v9, v18, 16, 1
	v_add3_u32 v9, v18, v9, s31
	s_waitcnt lgkmcnt(2)
	v_bfe_u32 v10, v20, 16, 1
	ds_read2_b32 v[42:43], v28 offset0:198 offset1:206
	v_lshrrev_b32_e32 v9, 16, v9
	v_add3_u32 v10, v20, v10, s31
	ds_read2_b32 v[44:45], v28 offset0:231 offset1:239
	s_mul_i32 s28, s37, 0x1900000
	v_and_or_b32 v9, v10, s35, v9
	s_waitcnt lgkmcnt(3)
	v_bfe_u32 v10, v22, 16, 1
	s_mul_hi_i32 s13, s37, 0x1900000
	s_add_u32 s28, s6, s28
	v_add3_u32 v10, v22, v10, s31
	s_waitcnt lgkmcnt(2)
	v_bfe_u32 v11, v40, 16, 1
	s_addc_u32 s13, s7, s13
	s_lshl_b64 s[14:15], s[14:15], 1
	v_lshrrev_b32_e32 v10, 16, v10
	v_add3_u32 v11, v40, v11, s31
	s_add_u32 s14, s28, s14
	v_and_or_b32 v10, v11, s35, v10
	s_waitcnt lgkmcnt(1)
	v_bfe_u32 v11, v42, 16, 1
	v_or_b32_e32 v46, s12, v24
	s_addc_u32 s15, s13, s15
	v_add3_u32 v11, v42, v11, s31
	s_waitcnt lgkmcnt(0)
	v_bfe_u32 v12, v44, 16, 1
	v_ashrrev_i32_e32 v47, 31, v46
	v_lshl_add_u64 v[14:15], s[14:15], 0, v[4:5]
	v_lshrrev_b32_e32 v11, 16, v11
	v_add3_u32 v12, v44, v12, s31
	v_lshlrev_b64 v[46:47], 12, v[46:47]
	v_and_or_b32 v11, v12, s35, v11
	v_lshl_add_u64 v[46:47], v[14:15], 0, v[46:47]
	global_store_dwordx4 v[46:47], v[8:11], off nt
	v_bfe_u32 v12, v45, 16, 1
	v_add3_u32 v12, v45, v12, s31
	v_bfe_u32 v8, v13, 16, 1
	v_add3_u32 v8, v13, v8, s31
	v_bfe_u32 v9, v17, 16, 1
	v_lshrrev_b32_e32 v8, 16, v8
	v_add3_u32 v9, v17, v9, s31
	v_and_or_b32 v8, v9, s35, v8
	v_bfe_u32 v9, v19, 16, 1
	v_add3_u32 v9, v19, v9, s31
	v_bfe_u32 v10, v21, 16, 1
	v_lshrrev_b32_e32 v9, 16, v9
	v_add3_u32 v10, v21, v10, s31
	v_and_or_b32 v9, v10, s35, v9
	v_bfe_u32 v10, v23, 16, 1
	v_add3_u32 v10, v23, v10, s31
	v_bfe_u32 v11, v41, 16, 1
	v_lshrrev_b32_e32 v10, 16, v10
	v_add3_u32 v11, v41, v11, s31
	v_and_or_b32 v10, v11, s35, v10
	v_bfe_u32 v11, v43, 16, 1
	v_add3_u32 v11, v43, v11, s31
	v_lshrrev_b32_e32 v11, 16, v11
	v_and_or_b32 v11, v12, s35, v11
	v_or_b32_e32 v12, s12, v29
	v_ashrrev_i32_e32 v13, 31, v12
	v_lshlrev_b64 v[12:13], 12, v[12:13]
	ds_read2_b32 v[16:17], v28 offset0:16 offset1:24
	v_lshl_add_u64 v[12:13], v[14:15], 0, v[12:13]
	global_store_dwordx4 v[12:13], v[8:11], off nt
	ds_read2_b32 v[12:13], v28 offset0:49 offset1:57
	ds_read2_b32 v[18:19], v28 offset0:82 offset1:90
	ds_read2_b32 v[20:21], v28 offset0:115 offset1:123
	s_waitcnt lgkmcnt(3)
	v_bfe_u32 v8, v16, 16, 1
	v_add3_u32 v8, v16, v8, s31
	s_waitcnt lgkmcnt(2)
	v_bfe_u32 v9, v12, 16, 1
	ds_read2_b32 v[22:23], v28 offset0:148 offset1:156
	v_lshrrev_b32_e32 v8, 16, v8
	v_add3_u32 v9, v12, v9, s31
	ds_read2_b32 v[40:41], v28 offset0:181 offset1:189
	v_and_or_b32 v8, v9, s35, v8
	s_waitcnt lgkmcnt(3)
	v_bfe_u32 v9, v18, 16, 1
	v_add3_u32 v9, v18, v9, s31
	s_waitcnt lgkmcnt(2)
	v_bfe_u32 v10, v20, 16, 1
	ds_read2_b32 v[42:43], v28 offset0:214 offset1:222
	v_lshrrev_b32_e32 v9, 16, v9
	v_add3_u32 v10, v20, v10, s31
	ds_read2_b32 v[44:45], v28 offset0:247 offset1:255
	v_and_or_b32 v9, v10, s35, v9
	s_waitcnt lgkmcnt(3)
	v_bfe_u32 v10, v22, 16, 1
	v_add3_u32 v10, v22, v10, s31
	s_waitcnt lgkmcnt(2)
	v_bfe_u32 v11, v40, 16, 1
	v_lshrrev_b32_e32 v10, 16, v10
	v_add3_u32 v11, v40, v11, s31
	v_and_or_b32 v10, v11, s35, v10
	s_waitcnt lgkmcnt(1)
	v_bfe_u32 v11, v42, 16, 1
	v_or_b32_e32 v46, s12, v30
	v_add3_u32 v11, v42, v11, s31
	s_waitcnt lgkmcnt(0)
	v_bfe_u32 v12, v44, 16, 1
	v_ashrrev_i32_e32 v47, 31, v46
	v_lshrrev_b32_e32 v11, 16, v11
	v_add3_u32 v12, v44, v12, s31
	v_lshlrev_b64 v[46:47], 12, v[46:47]
	v_and_or_b32 v11, v12, s35, v11
	v_lshl_add_u64 v[46:47], v[14:15], 0, v[46:47]
	global_store_dwordx4 v[46:47], v[8:11], off nt
	v_bfe_u32 v12, v45, 16, 1
	v_add3_u32 v12, v45, v12, s31
	v_bfe_u32 v8, v17, 16, 1
	v_add3_u32 v8, v17, v8, s31
	v_bfe_u32 v9, v13, 16, 1
	v_lshrrev_b32_e32 v8, 16, v8
	v_add3_u32 v9, v13, v9, s31
	v_and_or_b32 v8, v9, s35, v8
	v_bfe_u32 v9, v19, 16, 1
	v_add3_u32 v9, v19, v9, s31
	v_bfe_u32 v10, v21, 16, 1
	v_lshrrev_b32_e32 v9, 16, v9
	v_add3_u32 v10, v21, v10, s31
	v_and_or_b32 v9, v10, s35, v9
	v_bfe_u32 v10, v23, 16, 1
	v_add3_u32 v10, v23, v10, s31
	v_bfe_u32 v11, v41, 16, 1
	v_lshrrev_b32_e32 v10, 16, v10
	v_add3_u32 v11, v41, v11, s31
	v_and_or_b32 v10, v11, s35, v10
	v_bfe_u32 v11, v43, 16, 1
	v_add3_u32 v11, v43, v11, s31
	v_lshrrev_b32_e32 v11, 16, v11
	v_and_or_b32 v11, v12, s35, v11
	v_or_b32_e32 v12, s12, v31
	v_ashrrev_i32_e32 v13, 31, v12
	v_lshlrev_b64 v[12:13], 12, v[12:13]
	v_lshl_add_u64 v[12:13], v[14:15], 0, v[12:13]
	global_store_dwordx4 v[12:13], v[8:11], off nt
	s_waitcnt lgkmcnt(0)
	s_add_i32 s36, s36, s62
	s_cmpk_lt_i32 s36, 0x3040
	s_cbranch_scc1 .LBB0_19

; #define LAS __attribute__((address_space(3)))
; #define LDS_WAIT() asm volatile("s_waitcnt lgkmcnt(0)" ::: "memory")
; __device__ __forceinline__ void transpose_item(const float* W, int K, int N, bf16* WT, int k0, int n0, int drow0, LAS float* scr, int lane) {
;     ...
;     for (int i = 0; i < 32; ++i) { const int kk = 2 * i + (lane >> 5); scr[kk * 33 + (lane & 31)] = __builtin_nontemporal_load(W + (size_t)(k0 + kk) * N + n0 + (lane & 31)); }
;     LDS_WAIT(); asm volatile("" ::: "memory");
;     const int c = lane & 7;
; #pragma unroll
;     for (int j = 0; j < 4; ++j) { const int n = (lane >> 3) + 8 * j; const LAS float* s = scr + (8 * c) * 33 + n;
.LBB0_25:
	v_lshl_add_u64 v[42:43], v[22:23], 0, s[26:27]
	v_lshl_add_u64 v[44:45], v[20:21], 0, s[26:27]
	v_lshl_add_u64 v[46:47], v[18:19], 0, s[26:27]
	v_lshl_add_u64 v[48:49], v[16:17], 0, s[26:27]
	v_lshl_add_u64 v[50:51], v[14:15], 0, s[26:27]
	v_lshl_add_u64 v[52:53], v[12:13], 0, s[26:27]
	v_lshl_add_u64 v[54:55], v[10:11], 0, s[26:27]
	v_lshl_add_u64 v[56:57], v[8:9], 0, s[26:27]
	global_load_dword v41, v[42:43], off nt
	global_load_dword v58, v[44:45], off nt
	global_load_dword v59, v[46:47], off nt
	global_load_dword v60, v[48:49], off nt
	global_load_dword v61, v[50:51], off nt
	global_load_dword v62, v[52:53], off nt
	global_load_dword v63, v[54:55], off nt
	global_load_dword v64, v[56:57], off nt
	s_add_u32 s26, s26, 0x20000
	s_addc_u32 s27, s27, 0
	v_lshl_add_u64 v[42:43], v[22:23], 0, s[26:27]
	v_lshl_add_u64 v[44:45], v[20:21], 0, s[26:27]
	v_lshl_add_u64 v[46:47], v[18:19], 0, s[26:27]
	v_lshl_add_u64 v[48:49], v[16:17], 0, s[26:27]
	v_lshl_add_u64 v[50:51], v[14:15], 0, s[26:27]
	v_lshl_add_u64 v[52:53], v[12:13], 0, s[26:27]
	v_lshl_add_u64 v[54:55], v[10:11], 0, s[26:27]
	v_lshl_add_u64 v[56:57], v[8:9], 0, s[26:27]
	global_load_dword v65, v[42:43], off nt
	global_load_dword v66, v[44:45], off nt
	global_load_dword v67, v[46:47], off nt
	global_load_dword v68, v[48:49], off nt
	global_load_dword v69, v[50:51], off nt
	global_load_dword v70, v[52:53], off nt
	global_load_dword v71, v[54:55], off nt
	global_load_dword v72, v[56:57], off nt
	s_add_u32 s26, s26, 0x20000
	s_addc_u32 s27, s27, 0
	v_lshl_add_u64 v[42:43], v[22:23], 0, s[26:27]
	v_lshl_add_u64 v[44:45], v[20:21], 0, s[26:27]
	v_lshl_add_u64 v[46:47], v[18:19], 0, s[26:27]
	v_lshl_add_u64 v[48:49], v[16:17], 0, s[26:27]
	v_lshl_add_u64 v[50:51], v[14:15], 0, s[26:27]
	v_lshl_add_u64 v[52:53], v[12:13], 0, s[26:27]
	v_lshl_add_u64 v[54:55], v[10:11], 0, s[26:27]
	v_lshl_add_u64 v[56:57], v[8:9], 0, s[26:27]
	global_load_dword v73, v[42:43], off nt
	global_load_dword v74, v[44:45], off nt
	global_load_dword v75, v[46:47], off nt
	global_load_dword v76, v[48:49], off nt
	global_load_dword v77, v[50:51], off nt
	global_load_dword v78, v[52:53], off nt
	global_load_dword v79, v[54:55], off nt
	global_load_dword v80, v[56:57], off nt
	s_add_u32 s26, s26, 0x20000
	s_addc_u32 s27, s27, 0
	v_lshl_add_u64 v[42:43], v[22:23], 0, s[26:27]
	v_lshl_add_u64 v[44:45], v[20:21], 0, s[26:27]
	v_lshl_add_u64 v[46:47], v[18:19], 0, s[26:27]
	v_lshl_add_u64 v[48:49], v[16:17], 0, s[26:27]
	v_lshl_add_u64 v[50:51], v[14:15], 0, s[26:27]
	v_lshl_add_u64 v[52:53], v[12:13], 0, s[26:27]
	v_lshl_add_u64 v[54:55], v[10:11], 0, s[26:27]
	v_lshl_add_u64 v[56:57], v[8:9], 0, s[26:27]
	global_load_dword v81, v[42:43], off nt
	global_load_dword v82, v[44:45], off nt
	global_load_dword v83, v[46:47], off nt
	global_load_dword v84, v[48:49], off nt
	global_load_dword v85, v[50:51], off nt
	global_load_dword v86, v[52:53], off nt
	global_load_dword v87, v[54:55], off nt
	global_load_dword v88, v[56:57], off nt
	s_add_u32 s26, s26, 0x20000
	s_addc_u32 s27, s27, 0
	v_add_u32_e32 v89, 0x400, v40
	s_waitcnt vmcnt(30)
	ds_write2_b32 v40, v41, v58 offset1:66
	s_waitcnt vmcnt(28)
	ds_write2_b32 v40, v59, v60 offset0:132 offset1:198
	s_waitcnt vmcnt(26)
	ds_write2_b32 v89, v61, v62 offset0:8 offset1:74
	s_waitcnt vmcnt(24)
	ds_write2_b32 v89, v63, v64 offset0:140 offset1:206
	v_add_u32_e32 v40, 0x840, v40
	v_add_u32_e32 v89, 0x400, v40
	s_waitcnt vmcnt(22)
	ds_write2_b32 v40, v65, v66 offset1:66
	s_waitcnt vmcnt(20)
	ds_write2_b32 v40, v67, v68 offset0:132 offset1:198
	s_waitcnt vmcnt(18)
	ds_write2_b32 v89, v69, v70 offset0:8 offset1:74
	s_waitcnt vmcnt(16)
	ds_write2_b32 v89, v71, v72 offset0:140 offset1:206
	v_add_u32_e32 v40, 0x840, v40
	v_add_u32_e32 v89, 0x400, v40
	s_waitcnt vmcnt(14)
	ds_write2_b32 v40, v73, v74 offset1:66
	s_waitcnt vmcnt(12)
	ds_write2_b32 v40, v75, v76 offset0:132 offset1:198
	s_waitcnt vmcnt(10)
	ds_write2_b32 v89, v77, v78 offset0:8 offset1:74
	s_waitcnt vmcnt(8)
	ds_write2_b32 v89, v79, v80 offset0:140 offset1:206
	v_add_u32_e32 v40, 0x840, v40
	v_add_u32_e32 v89, 0x400, v40
	s_waitcnt vmcnt(6)
	ds_write2_b32 v40, v81, v82 offset1:66
	s_waitcnt vmcnt(4)
	ds_write2_b32 v40, v83, v84 offset0:132 offset1:198
	s_waitcnt vmcnt(2)
	ds_write2_b32 v89, v85, v86 offset0:8 offset1:74
	s_waitcnt vmcnt(0)
	ds_write2_b32 v89, v87, v88 offset0:140 offset1:206
	v_add_u32_e32 v40, 0x840, v40
	s_waitcnt lgkmcnt(0)
	ds_read2_b32 v[12:13], v28 offset1:8
	ds_read2_b32 v[16:17], v28 offset0:33 offset1:41
	ds_read2_b32 v[18:19], v28 offset0:66 offset1:74
	ds_read2_b32 v[20:21], v28 offset0:99 offset1:107
	ds_read2_b32 v[22:23], v28 offset0:132 offset1:140
	s_waitcnt lgkmcnt(4)
	v_bfe_u32 v8, v12, 16, 1
	v_add3_u32 v8, v12, v8, s30
	s_waitcnt lgkmcnt(3)
; #define LAS __attribute__((address_space(3)))
; #define LDS_WAIT() asm volatile("s_waitcnt lgkmcnt(0)" ::: "memory")
; __device__ __forceinline__ unsigned pk2(float lo, float hi) { return f2bf(lo) | (f2bf(hi) << 16); }
; __device__ __forceinline__ void transpose_item(const float* W, int K, int N, bf16* WT, int k0, int n0, int drow0, LAS float* scr, int lane) {
;     ...
;     const int c = lane & 7;
; #pragma unroll
;     for (int j = 0; j < 4; ++j) { const int n = (lane >> 3) + 8 * j; const LAS float* s = scr + (8 * c) * 33 + n;
;         v4u o; o.x = pk2(s[0 * 33], s[1 * 33]); o.y = pk2(s[2 * 33], s[3 * 33]); o.z = pk2(s[4 * 33], s[5 * 33]); o.w = pk2(s[6 * 33], s[7 * 33]);
;         __builtin_nontemporal_store(o, (v4u*)(WT + (size_t)(drow0 + n) * K + k0 + 8 * c)); }
;     LDS_WAIT(); asm volatile("" ::: "memory");
; template <bool GU>
; __device__ __forceinline__ void transpose_family(const float* W, int nmat, int K, int N, bf16* WT, size_t dstride, LAS float* scr, int gw, int NGW, int lane) {
;     ...
;     for (int it = gw; it < total; it += NGW) {
;         const int mi = it / per, r = it % per, kb = r / nblk, nb = r % nblk, n0 = nb * 32;
;         int drow0 = n0;
;         if (GU) { const int j = n0 < DFF ? n0 : n0 - DFF; drow0 = (j >> 7) * 256 + (n0 < DFF ? 0 : 128) + (j & 127); }
;         transpose_item(W + (size_t)mi * K * N, K, N, WT + (size_t)mi * dstride, kb * 64, n0, drow0, scr, lane);
	v_bfe_u32 v9, v16, 16, 1
	v_lshrrev_b32_e32 v8, 16, v8
	v_add3_u32 v9, v16, v9, s30
	ds_read2_b32 v[40:41], v28 offset0:165 offset1:173
	v_and_or_b32 v8, v9, s31, v8
	s_waitcnt lgkmcnt(3)
	v_bfe_u32 v9, v18, 16, 1
	v_add3_u32 v9, v18, v9, s30
	s_waitcnt lgkmcnt(2)
	v_bfe_u32 v10, v20, 16, 1
	ds_read2_b32 v[42:43], v28 offset0:198 offset1:206
	v_lshrrev_b32_e32 v9, 16, v9
	v_add3_u32 v10, v20, v10, s30
	ds_read2_b32 v[44:45], v28 offset0:231 offset1:239
	s_lshl_b64 s[12:13], s[12:13], 23
	v_and_or_b32 v9, v10, s31, v9
	s_waitcnt lgkmcnt(3)
	v_bfe_u32 v10, v22, 16, 1
	s_add_u32 s9, s28, s12
	v_add3_u32 v10, v22, v10, s30
	s_waitcnt lgkmcnt(2)
	v_bfe_u32 v11, v40, 16, 1
	s_addc_u32 s26, s29, s13
	s_lshl_b64 s[12:13], s[14:15], 1
	v_lshrrev_b32_e32 v10, 16, v10
	v_add3_u32 v11, v40, v11, s30
	s_add_u32 s12, s9, s12
	v_and_or_b32 v10, v11, s31, v10
	s_waitcnt lgkmcnt(1)
	v_bfe_u32 v11, v42, 16, 1
	v_or_b32_e32 v46, s8, v24
	s_addc_u32 s13, s26, s13
	v_add3_u32 v11, v42, v11, s30
	s_waitcnt lgkmcnt(0)
	v_bfe_u32 v12, v44, 16, 1
	v_ashrrev_i32_e32 v47, 31, v46
	v_lshl_add_u64 v[14:15], s[12:13], 0, v[4:5]
	v_lshrrev_b32_e32 v11, 16, v11
	v_add3_u32 v12, v44, v12, s30
	v_lshlrev_b64 v[46:47], 12, v[46:47]
	v_and_or_b32 v11, v12, s31, v11
	v_lshl_add_u64 v[46:47], v[14:15], 0, v[46:47]
	global_store_dwordx4 v[46:47], v[8:11], off nt
	v_bfe_u32 v12, v45, 16, 1
	v_add3_u32 v12, v45, v12, s30
	v_bfe_u32 v8, v13, 16, 1
	v_add3_u32 v8, v13, v8, s30
	v_bfe_u32 v9, v17, 16, 1
	v_lshrrev_b32_e32 v8, 16, v8
	v_add3_u32 v9, v17, v9, s30
	v_and_or_b32 v8, v9, s31, v8
	v_bfe_u32 v9, v19, 16, 1
	v_add3_u32 v9, v19, v9, s30
	v_bfe_u32 v10, v21, 16, 1
	v_lshrrev_b32_e32 v9, 16, v9
	v_add3_u32 v10, v21, v10, s30
	v_and_or_b32 v9, v10, s31, v9
	v_bfe_u32 v10, v23, 16, 1
	v_add3_u32 v10, v23, v10, s30
	v_bfe_u32 v11, v41, 16, 1
	v_lshrrev_b32_e32 v10, 16, v10
	v_add3_u32 v11, v41, v11, s30
	v_and_or_b32 v10, v11, s31, v10
	v_bfe_u32 v11, v43, 16, 1
	v_add3_u32 v11, v43, v11, s30
	v_lshrrev_b32_e32 v11, 16, v11
	v_and_or_b32 v11, v12, s31, v11
	v_or_b32_e32 v12, s8, v29
	v_ashrrev_i32_e32 v13, 31, v12
	v_lshlrev_b64 v[12:13], 12, v[12:13]
	ds_read2_b32 v[16:17], v28 offset0:16 offset1:24
	v_lshl_add_u64 v[12:13], v[14:15], 0, v[12:13]
	global_store_dwordx4 v[12:13], v[8:11], off nt
	ds_read2_b32 v[12:13], v28 offset0:49 offset1:57
	ds_read2_b32 v[18:19], v28 offset0:82 offset1:90
	ds_read2_b32 v[20:21], v28 offset0:115 offset1:123
	s_waitcnt lgkmcnt(3)
	v_bfe_u32 v8, v16, 16, 1
	v_add3_u32 v8, v16, v8, s30
	s_waitcnt lgkmcnt(2)
	v_bfe_u32 v9, v12, 16, 1
	ds_read2_b32 v[22:23], v28 offset0:148 offset1:156
	v_lshrrev_b32_e32 v8, 16, v8
	v_add3_u32 v9, v12, v9, s30
	ds_read2_b32 v[40:41], v28 offset0:181 offset1:189
	v_and_or_b32 v8, v9, s31, v8
	s_waitcnt lgkmcnt(3)
	v_bfe_u32 v9, v18, 16, 1
	v_add3_u32 v9, v18, v9, s30
	s_waitcnt lgkmcnt(2)
	v_bfe_u32 v10, v20, 16, 1
	ds_read2_b32 v[42:43], v28 offset0:214 offset1:222
	v_lshrrev_b32_e32 v9, 16, v9
	v_add3_u32 v10, v20, v10, s30
	ds_read2_b32 v[44:45], v28 offset0:247 offset1:255
	v_and_or_b32 v9, v10, s31, v9
	s_waitcnt lgkmcnt(3)
	v_bfe_u32 v10, v22, 16, 1
	v_add3_u32 v10, v22, v10, s30
	s_waitcnt lgkmcnt(2)
	v_bfe_u32 v11, v40, 16, 1
	v_lshrrev_b32_e32 v10, 16, v10
	v_add3_u32 v11, v40, v11, s30
	v_and_or_b32 v10, v11, s31, v10
	s_waitcnt lgkmcnt(1)
	v_bfe_u32 v11, v42, 16, 1
	v_or_b32_e32 v46, s8, v30
	v_add3_u32 v11, v42, v11, s30
	s_waitcnt lgkmcnt(0)
	v_bfe_u32 v12, v44, 16, 1
	v_ashrrev_i32_e32 v47, 31, v46
	v_lshrrev_b32_e32 v11, 16, v11
	v_add3_u32 v12, v44, v12, s30
	v_lshlrev_b64 v[46:47], 12, v[46:47]
	v_and_or_b32 v11, v12, s31, v11
	v_lshl_add_u64 v[46:47], v[14:15], 0, v[46:47]
	global_store_dwordx4 v[46:47], v[8:11], off nt
	v_bfe_u32 v12, v45, 16, 1
	v_add3_u32 v12, v45, v12, s30
	v_bfe_u32 v8, v17, 16, 1
	v_add3_u32 v8, v17, v8, s30
	v_bfe_u32 v9, v13, 16, 1
	v_lshrrev_b32_e32 v8, 16, v8
	v_add3_u32 v9, v13, v9, s30
	v_and_or_b32 v8, v9, s31, v8
	v_bfe_u32 v9, v19, 16, 1
	v_add3_u32 v9, v19, v9, s30
	v_bfe_u32 v10, v21, 16, 1
	v_lshrrev_b32_e32 v9, 16, v9
	v_add3_u32 v10, v21, v10, s30
	v_and_or_b32 v9, v10, s31, v9
	v_bfe_u32 v10, v23, 16, 1
	v_add3_u32 v10, v23, v10, s30
	v_bfe_u32 v11, v41, 16, 1
	v_lshrrev_b32_e32 v10, 16, v10
	v_add3_u32 v11, v41, v11, s30
	v_and_or_b32 v10, v11, s31, v10
	v_bfe_u32 v11, v43, 16, 1
	v_add3_u32 v11, v43, v11, s30
	v_lshrrev_b32_e32 v11, 16, v11
	v_and_or_b32 v11, v12, s31, v11
	v_or_b32_e32 v12, s8, v31
	v_ashrrev_i32_e32 v13, 31, v12
	v_lshlrev_b64 v[12:13], 12, v[12:13]
	v_lshl_add_u64 v[12:13], v[14:15], 0, v[12:13]
	global_store_dwordx4 v[12:13], v[8:11], off nt
	s_waitcnt lgkmcnt(0)
	s_add_i32 s35, s35, s62
	s_cmpk_lt_i32 s35, 0x1000
	s_cbranch_scc1 .LBB0_24

; #define LAS __attribute__((address_space(3)))
; #define LDS_WAIT() asm volatile("s_waitcnt lgkmcnt(0)" ::: "memory")
; __device__ __forceinline__ void transpose_item(const float* W, int K, int N, bf16* WT, int k0, int n0, int drow0, LAS float* scr, int lane) {
;     ...
;     for (int i = 0; i < 32; ++i) { const int kk = 2 * i + (lane >> 5); scr[kk * 33 + (lane & 31)] = __builtin_nontemporal_load(W + (size_t)(k0 + kk) * N + n0 + (lane & 31)); }
;     LDS_WAIT(); asm volatile("" ::: "memory");
;     const int c = lane & 7;
; #pragma unroll
;     for (int j = 0; j < 4; ++j) { const int n = (lane >> 3) + 8 * j; const LAS float* s = scr + (8 * c) * 33 + n;
.LBB0_30:
	v_lshl_add_u64 v[42:43], v[22:23], 0, s[12:13]
	v_lshl_add_u64 v[44:45], v[20:21], 0, s[12:13]
	v_lshl_add_u64 v[46:47], v[18:19], 0, s[12:13]
	v_lshl_add_u64 v[48:49], v[16:17], 0, s[12:13]
	v_lshl_add_u64 v[50:51], v[14:15], 0, s[12:13]
	v_lshl_add_u64 v[52:53], v[12:13], 0, s[12:13]
	v_lshl_add_u64 v[54:55], v[10:11], 0, s[12:13]
	v_lshl_add_u64 v[56:57], v[8:9], 0, s[12:13]
	global_load_dword v41, v[42:43], off nt
	global_load_dword v58, v[44:45], off nt
	global_load_dword v59, v[46:47], off nt
	global_load_dword v60, v[48:49], off nt
	global_load_dword v61, v[50:51], off nt
	global_load_dword v62, v[52:53], off nt
	global_load_dword v63, v[54:55], off nt
	global_load_dword v64, v[56:57], off nt
	s_add_u32 s12, s12, 0xb0000
	s_addc_u32 s13, s13, 0
	v_lshl_add_u64 v[42:43], v[22:23], 0, s[12:13]
	v_lshl_add_u64 v[44:45], v[20:21], 0, s[12:13]
	v_lshl_add_u64 v[46:47], v[18:19], 0, s[12:13]
	v_lshl_add_u64 v[48:49], v[16:17], 0, s[12:13]
	v_lshl_add_u64 v[50:51], v[14:15], 0, s[12:13]
	v_lshl_add_u64 v[52:53], v[12:13], 0, s[12:13]
	v_lshl_add_u64 v[54:55], v[10:11], 0, s[12:13]
	v_lshl_add_u64 v[56:57], v[8:9], 0, s[12:13]
	global_load_dword v65, v[42:43], off nt
	global_load_dword v66, v[44:45], off nt
	global_load_dword v67, v[46:47], off nt
	global_load_dword v68, v[48:49], off nt
	global_load_dword v69, v[50:51], off nt
	global_load_dword v70, v[52:53], off nt
	global_load_dword v71, v[54:55], off nt
	global_load_dword v72, v[56:57], off nt
	s_add_u32 s12, s12, 0xb0000
	s_addc_u32 s13, s13, 0
	v_lshl_add_u64 v[42:43], v[22:23], 0, s[12:13]
	v_lshl_add_u64 v[44:45], v[20:21], 0, s[12:13]
	v_lshl_add_u64 v[46:47], v[18:19], 0, s[12:13]
	v_lshl_add_u64 v[48:49], v[16:17], 0, s[12:13]
	v_lshl_add_u64 v[50:51], v[14:15], 0, s[12:13]
	v_lshl_add_u64 v[52:53], v[12:13], 0, s[12:13]
	v_lshl_add_u64 v[54:55], v[10:11], 0, s[12:13]
	v_lshl_add_u64 v[56:57], v[8:9], 0, s[12:13]
	global_load_dword v73, v[42:43], off nt
	global_load_dword v74, v[44:45], off nt
	global_load_dword v75, v[46:47], off nt
	global_load_dword v76, v[48:49], off nt
	global_load_dword v77, v[50:51], off nt
	global_load_dword v78, v[52:53], off nt
	global_load_dword v79, v[54:55], off nt
	global_load_dword v80, v[56:57], off nt
	s_add_u32 s12, s12, 0xb0000
	s_addc_u32 s13, s13, 0
	v_lshl_add_u64 v[42:43], v[22:23], 0, s[12:13]
	v_lshl_add_u64 v[44:45], v[20:21], 0, s[12:13]
	v_lshl_add_u64 v[46:47], v[18:19], 0, s[12:13]
	v_lshl_add_u64 v[48:49], v[16:17], 0, s[12:13]
	v_lshl_add_u64 v[50:51], v[14:15], 0, s[12:13]
	v_lshl_add_u64 v[52:53], v[12:13], 0, s[12:13]
	v_lshl_add_u64 v[54:55], v[10:11], 0, s[12:13]
	v_lshl_add_u64 v[56:57], v[8:9], 0, s[12:13]
	global_load_dword v81, v[42:43], off nt
	global_load_dword v82, v[44:45], off nt
	global_load_dword v83, v[46:47], off nt
	global_load_dword v84, v[48:49], off nt
	global_load_dword v85, v[50:51], off nt
	global_load_dword v86, v[52:53], off nt
	global_load_dword v87, v[54:55], off nt
	global_load_dword v88, v[56:57], off nt
	s_add_u32 s12, s12, 0xb0000
	s_addc_u32 s13, s13, 0
	v_add_u32_e32 v89, 0x400, v40
	s_waitcnt vmcnt(30)
	ds_write2_b32 v40, v41, v58 offset1:66
	s_waitcnt vmcnt(28)
	ds_write2_b32 v40, v59, v60 offset0:132 offset1:198
	s_waitcnt vmcnt(26)
	ds_write2_b32 v89, v61, v62 offset0:8 offset1:74
	s_waitcnt vmcnt(24)
	ds_write2_b32 v89, v63, v64 offset0:140 offset1:206
	v_add_u32_e32 v40, 0x840, v40
	v_add_u32_e32 v89, 0x400, v40
	s_waitcnt vmcnt(22)
	ds_write2_b32 v40, v65, v66 offset1:66
	s_waitcnt vmcnt(20)
	ds_write2_b32 v40, v67, v68 offset0:132 offset1:198
	s_waitcnt vmcnt(18)
	ds_write2_b32 v89, v69, v70 offset0:8 offset1:74
	s_waitcnt vmcnt(16)
	ds_write2_b32 v89, v71, v72 offset0:140 offset1:206
	v_add_u32_e32 v40, 0x840, v40
	v_add_u32_e32 v89, 0x400, v40
	s_waitcnt vmcnt(14)
	ds_write2_b32 v40, v73, v74 offset1:66
	s_waitcnt vmcnt(12)
	ds_write2_b32 v40, v75, v76 offset0:132 offset1:198
	s_waitcnt vmcnt(10)
	ds_write2_b32 v89, v77, v78 offset0:8 offset1:74
	s_waitcnt vmcnt(8)
	ds_write2_b32 v89, v79, v80 offset0:140 offset1:206
	v_add_u32_e32 v40, 0x840, v40
	v_add_u32_e32 v89, 0x400, v40
	s_waitcnt vmcnt(6)
	ds_write2_b32 v40, v81, v82 offset1:66
	s_waitcnt vmcnt(4)
	ds_write2_b32 v40, v83, v84 offset0:132 offset1:198
	s_waitcnt vmcnt(2)
	ds_write2_b32 v89, v85, v86 offset0:8 offset1:74
	s_waitcnt vmcnt(0)
	ds_write2_b32 v89, v87, v88 offset0:140 offset1:206
	v_add_u32_e32 v40, 0x840, v40
	s_waitcnt lgkmcnt(0)
	ds_read2_b32 v[12:13], v28 offset1:8
	ds_read2_b32 v[16:17], v28 offset0:33 offset1:41
	ds_read2_b32 v[18:19], v28 offset0:66 offset1:74
	ds_read2_b32 v[20:21], v28 offset0:99 offset1:107
	s_add_i32 s11, s10, 0xffffea00
	s_waitcnt lgkmcnt(3)
	v_bfe_u32 v8, v12, 16, 1
	v_add3_u32 v8, v12, v8, s27
	s_waitcnt lgkmcnt(2)
; #define LAS __attribute__((address_space(3)))
; #define LDS_WAIT() asm volatile("s_waitcnt lgkmcnt(0)" ::: "memory")
; __device__ __forceinline__ unsigned pk2(float lo, float hi) { return f2bf(lo) | (f2bf(hi) << 16); }
; __device__ __forceinline__ void transpose_item(const float* W, int K, int N, bf16* WT, int k0, int n0, int drow0, LAS float* scr, int lane) {
;     ...
;     const int c = lane & 7;
; #pragma unroll
;     for (int j = 0; j < 4; ++j) { const int n = (lane >> 3) + 8 * j; const LAS float* s = scr + (8 * c) * 33 + n;
;         v4u o; o.x = pk2(s[0 * 33], s[1 * 33]); o.y = pk2(s[2 * 33], s[3 * 33]); o.z = pk2(s[4 * 33], s[5 * 33]); o.w = pk2(s[6 * 33], s[7 * 33]);
;         __builtin_nontemporal_store(o, (v4u*)(WT + (size_t)(drow0 + n) * K + k0 + 8 * c)); }
;     LDS_WAIT(); asm volatile("" ::: "memory");
; }
; template <bool GU>
; __device__ __forceinline__ void transpose_family(const float* W, int nmat, int K, int N, bf16* WT, size_t dstride, LAS float* scr, int gw, int NGW, int lane) {
;     const int nblk = N / 32, per = (K / 64) * nblk, total = nmat * per;
;     for (int it = gw; it < total; it += NGW) {
;         const int mi = it / per, r = it % per, kb = r / nblk, nb = r % nblk, n0 = nb * 32;
;         int drow0 = n0;
;         if (GU) { const int j = n0 < DFF ? n0 : n0 - DFF; drow0 = (j >> 7) * 256 + (n0 < DFF ? 0 : 128) + (j & 127); }
;         transpose_item(W + (size_t)mi * K * N, K, N, WT + (size_t)mi * dstride, kb * 64, n0, drow0, scr, lane);
	v_bfe_u32 v9, v16, 16, 1
	ds_read2_b32 v[22:23], v28 offset0:132 offset1:140
	s_cmpk_lt_i32 s31, 0xb0
	v_lshrrev_b32_e32 v8, 16, v8
	v_add3_u32 v9, v16, v9, s27
	ds_read2_b32 v[40:41], v28 offset0:165 offset1:173
	s_cselect_b32 s10, s10, s11
	v_and_or_b32 v8, v9, s28, v8
	s_waitcnt lgkmcnt(3)
	v_bfe_u32 v9, v18, 16, 1
	s_cselect_b32 s11, 0, 0x80
	s_lshl_b32 s12, s10, 1
	s_and_b32 s10, s10, 0x60
	v_add3_u32 v9, v18, v9, s27
	s_waitcnt lgkmcnt(2)
	v_bfe_u32 v10, v20, 16, 1
	ds_read2_b32 v[42:43], v28 offset0:198 offset1:206
	s_or_b32 s10, s10, s11
	s_and_b32 s12, s12, 0xffffff00
	v_lshrrev_b32_e32 v9, 16, v9
	v_add3_u32 v10, v20, v10, s27
	ds_read2_b32 v[44:45], v28 offset0:231 offset1:239
	s_mul_i32 s13, s30, 0x2c00000
	s_or_b32 s10, s10, s12
	v_and_or_b32 v9, v10, s28, v9
	s_waitcnt lgkmcnt(3)
	v_bfe_u32 v10, v22, 16, 1
	s_mul_hi_i32 s11, s30, 0x2c00000
	s_add_u32 s12, s14, s13
	v_add3_u32 v10, v22, v10, s27
	s_waitcnt lgkmcnt(2)
	v_bfe_u32 v11, v40, 16, 1
	s_addc_u32 s11, s15, s11
	s_lshl_b64 s[8:9], s[8:9], 1
	v_lshrrev_b32_e32 v10, 16, v10
	v_add3_u32 v11, v40, v11, s27
	s_add_u32 s8, s12, s8
	v_and_or_b32 v10, v11, s28, v10
	s_waitcnt lgkmcnt(1)
	v_bfe_u32 v11, v42, 16, 1
	v_or_b32_e32 v46, s10, v24
	s_addc_u32 s9, s11, s9
	v_add3_u32 v11, v42, v11, s27
	s_waitcnt lgkmcnt(0)
	v_bfe_u32 v12, v44, 16, 1
	v_ashrrev_i32_e32 v47, 31, v46
	v_lshl_add_u64 v[14:15], s[8:9], 0, v[4:5]
	v_lshrrev_b32_e32 v11, 16, v11
	v_add3_u32 v12, v44, v12, s27
	v_lshlrev_b64 v[46:47], 12, v[46:47]
	v_and_or_b32 v11, v12, s28, v11
	v_lshl_add_u64 v[46:47], v[14:15], 0, v[46:47]
	global_store_dwordx4 v[46:47], v[8:11], off nt
	v_bfe_u32 v12, v45, 16, 1
	v_add3_u32 v12, v45, v12, s27
	v_bfe_u32 v8, v13, 16, 1
	v_add3_u32 v8, v13, v8, s27
	v_bfe_u32 v9, v17, 16, 1
	v_lshrrev_b32_e32 v8, 16, v8
	v_add3_u32 v9, v17, v9, s27
	v_and_or_b32 v8, v9, s28, v8
	v_bfe_u32 v9, v19, 16, 1
	v_add3_u32 v9, v19, v9, s27
	v_bfe_u32 v10, v21, 16, 1
	v_lshrrev_b32_e32 v9, 16, v9
	v_add3_u32 v10, v21, v10, s27
	v_and_or_b32 v9, v10, s28, v9
	v_bfe_u32 v10, v23, 16, 1
	v_add3_u32 v10, v23, v10, s27
	v_bfe_u32 v11, v41, 16, 1
	v_lshrrev_b32_e32 v10, 16, v10
	v_add3_u32 v11, v41, v11, s27
	v_and_or_b32 v10, v11, s28, v10
	v_bfe_u32 v11, v43, 16, 1
	v_add3_u32 v11, v43, v11, s27
	v_lshrrev_b32_e32 v11, 16, v11
	v_and_or_b32 v11, v12, s28, v11
	v_or_b32_e32 v12, s10, v29
	v_ashrrev_i32_e32 v13, 31, v12
	v_lshlrev_b64 v[12:13], 12, v[12:13]
	ds_read2_b32 v[16:17], v28 offset0:16 offset1:24
	v_lshl_add_u64 v[12:13], v[14:15], 0, v[12:13]
	global_store_dwordx4 v[12:13], v[8:11], off nt
	ds_read2_b32 v[12:13], v28 offset0:49 offset1:57
	ds_read2_b32 v[18:19], v28 offset0:82 offset1:90
	ds_read2_b32 v[20:21], v28 offset0:115 offset1:123
	s_waitcnt lgkmcnt(3)
	v_bfe_u32 v8, v16, 16, 1
	v_add3_u32 v8, v16, v8, s27
	s_waitcnt lgkmcnt(2)
	v_bfe_u32 v9, v12, 16, 1
	ds_read2_b32 v[22:23], v28 offset0:148 offset1:156
	v_lshrrev_b32_e32 v8, 16, v8
	v_add3_u32 v9, v12, v9, s27
	ds_read2_b32 v[40:41], v28 offset0:181 offset1:189
	v_and_or_b32 v8, v9, s28, v8
	s_waitcnt lgkmcnt(3)
	v_bfe_u32 v9, v18, 16, 1
	v_add3_u32 v9, v18, v9, s27
	s_waitcnt lgkmcnt(2)
	v_bfe_u32 v10, v20, 16, 1
	ds_read2_b32 v[42:43], v28 offset0:214 offset1:222
	v_lshrrev_b32_e32 v9, 16, v9
	v_add3_u32 v10, v20, v10, s27
	ds_read2_b32 v[44:45], v28 offset0:247 offset1:255
	v_and_or_b32 v9, v10, s28, v9
	s_waitcnt lgkmcnt(3)
	v_bfe_u32 v10, v22, 16, 1
	v_add3_u32 v10, v22, v10, s27
	s_waitcnt lgkmcnt(2)
	v_bfe_u32 v11, v40, 16, 1
	v_lshrrev_b32_e32 v10, 16, v10
	v_add3_u32 v11, v40, v11, s27
	v_and_or_b32 v10, v11, s28, v10
	s_waitcnt lgkmcnt(1)
	v_bfe_u32 v11, v42, 16, 1
	v_or_b32_e32 v46, s10, v30
	v_add3_u32 v11, v42, v11, s27
	s_waitcnt lgkmcnt(0)
	v_bfe_u32 v12, v44, 16, 1
	v_ashrrev_i32_e32 v47, 31, v46
	v_lshrrev_b32_e32 v11, 16, v11
	v_add3_u32 v12, v44, v12, s27
	v_lshlrev_b64 v[46:47], 12, v[46:47]
	v_and_or_b32 v11, v12, s28, v11
	v_lshl_add_u64 v[46:47], v[14:15], 0, v[46:47]
	global_store_dwordx4 v[46:47], v[8:11], off nt
	v_bfe_u32 v12, v45, 16, 1
	v_add3_u32 v12, v45, v12, s27
	v_bfe_u32 v8, v17, 16, 1
	v_add3_u32 v8, v17, v8, s27
	v_bfe_u32 v9, v13, 16, 1
	v_lshrrev_b32_e32 v8, 16, v8
	v_add3_u32 v9, v13, v9, s27
	v_and_or_b32 v8, v9, s28, v8
	v_bfe_u32 v9, v19, 16, 1
	v_add3_u32 v9, v19, v9, s27
	v_bfe_u32 v10, v21, 16, 1
	v_lshrrev_b32_e32 v9, 16, v9
	v_add3_u32 v10, v21, v10, s27
	v_and_or_b32 v9, v10, s28, v9
	v_bfe_u32 v10, v23, 16, 1
	v_add3_u32 v10, v23, v10, s27
	v_bfe_u32 v11, v41, 16, 1
	v_lshrrev_b32_e32 v10, 16, v10
	v_add3_u32 v11, v41, v11, s27
	v_and_or_b32 v10, v11, s28, v10
	v_bfe_u32 v11, v43, 16, 1
	v_add3_u32 v11, v43, v11, s27
	v_lshrrev_b32_e32 v11, 16, v11
	v_and_or_b32 v11, v12, s28, v11
	v_or_b32_e32 v12, s10, v31
	v_ashrrev_i32_e32 v13, 31, v12
	v_lshlrev_b64 v[12:13], 12, v[12:13]
	v_lshl_add_u64 v[12:13], v[14:15], 0, v[12:13]
	global_store_dwordx4 v[12:13], v[8:11], off nt
	s_waitcnt lgkmcnt(0)
	s_add_i32 s29, s29, s62
	s_cmp_lt_i32 s29, 0xb000
	s_cbranch_scc1 .LBB0_29

; #define LAS __attribute__((address_space(3)))
; #define LDS_WAIT() asm volatile("s_waitcnt lgkmcnt(0)" ::: "memory")
; __device__ __forceinline__ void transpose_item(const float* W, int K, int N, bf16* WT, int k0, int n0, int drow0, LAS float* scr, int lane) {
;     ...
;     for (int i = 0; i < 32; ++i) { const int kk = 2 * i + (lane >> 5); scr[kk * 33 + (lane & 31)] = __builtin_nontemporal_load(W + (size_t)(k0 + kk) * N + n0 + (lane & 31)); }
;     LDS_WAIT(); asm volatile("" ::: "memory");
;     const int c = lane & 7;
; #pragma unroll
;     for (int j = 0; j < 4; ++j) { const int n = (lane >> 3) + 8 * j; const LAS float* s = scr + (8 * c) * 33 + n;
.LBB0_35:
	v_lshl_add_u64 v[38:39], v[22:23], 0, s[12:13]
	v_lshl_add_u64 v[40:41], v[20:21], 0, s[12:13]
	v_lshl_add_u64 v[42:43], v[18:19], 0, s[12:13]
	v_lshl_add_u64 v[44:45], v[16:17], 0, s[12:13]
	v_lshl_add_u64 v[46:47], v[14:15], 0, s[12:13]
	v_lshl_add_u64 v[48:49], v[12:13], 0, s[12:13]
	v_lshl_add_u64 v[50:51], v[10:11], 0, s[12:13]
	v_lshl_add_u64 v[52:53], v[8:9], 0, s[12:13]
	global_load_dword v54, v[38:39], off nt
	global_load_dword v55, v[40:41], off nt
	global_load_dword v56, v[42:43], off nt
	global_load_dword v57, v[44:45], off nt
	global_load_dword v58, v[46:47], off nt
	global_load_dword v59, v[48:49], off nt
	global_load_dword v60, v[50:51], off nt
	global_load_dword v61, v[52:53], off nt
	s_add_u32 s12, s12, 0x20000
	s_addc_u32 s13, s13, 0
	v_lshl_add_u64 v[38:39], v[22:23], 0, s[12:13]
	v_lshl_add_u64 v[40:41], v[20:21], 0, s[12:13]
	v_lshl_add_u64 v[42:43], v[18:19], 0, s[12:13]
	v_lshl_add_u64 v[44:45], v[16:17], 0, s[12:13]
	v_lshl_add_u64 v[46:47], v[14:15], 0, s[12:13]
	v_lshl_add_u64 v[48:49], v[12:13], 0, s[12:13]
	v_lshl_add_u64 v[50:51], v[10:11], 0, s[12:13]
	v_lshl_add_u64 v[52:53], v[8:9], 0, s[12:13]
	global_load_dword v65, v[38:39], off nt
	global_load_dword v66, v[40:41], off nt
	global_load_dword v67, v[42:43], off nt
	global_load_dword v68, v[44:45], off nt
	global_load_dword v69, v[46:47], off nt
	global_load_dword v70, v[48:49], off nt
	global_load_dword v71, v[50:51], off nt
	global_load_dword v72, v[52:53], off nt
	s_add_u32 s12, s12, 0x20000
	s_addc_u32 s13, s13, 0
	v_lshl_add_u64 v[38:39], v[22:23], 0, s[12:13]
	v_lshl_add_u64 v[40:41], v[20:21], 0, s[12:13]
	v_lshl_add_u64 v[42:43], v[18:19], 0, s[12:13]
	v_lshl_add_u64 v[44:45], v[16:17], 0, s[12:13]
	v_lshl_add_u64 v[46:47], v[14:15], 0, s[12:13]
	v_lshl_add_u64 v[48:49], v[12:13], 0, s[12:13]
	v_lshl_add_u64 v[50:51], v[10:11], 0, s[12:13]
	v_lshl_add_u64 v[52:53], v[8:9], 0, s[12:13]
	global_load_dword v73, v[38:39], off nt
	global_load_dword v74, v[40:41], off nt
	global_load_dword v75, v[42:43], off nt
	global_load_dword v76, v[44:45], off nt
	global_load_dword v77, v[46:47], off nt
	global_load_dword v78, v[48:49], off nt
	global_load_dword v79, v[50:51], off nt
	global_load_dword v80, v[52:53], off nt
	s_add_u32 s12, s12, 0x20000
	s_addc_u32 s13, s13, 0
	v_lshl_add_u64 v[38:39], v[22:23], 0, s[12:13]
	v_lshl_add_u64 v[40:41], v[20:21], 0, s[12:13]
	v_lshl_add_u64 v[42:43], v[18:19], 0, s[12:13]
	v_lshl_add_u64 v[44:45], v[16:17], 0, s[12:13]
	v_lshl_add_u64 v[46:47], v[14:15], 0, s[12:13]
	v_lshl_add_u64 v[48:49], v[12:13], 0, s[12:13]
	v_lshl_add_u64 v[50:51], v[10:11], 0, s[12:13]
	v_lshl_add_u64 v[52:53], v[8:9], 0, s[12:13]
	global_load_dword v81, v[38:39], off nt
	global_load_dword v82, v[40:41], off nt
	global_load_dword v83, v[42:43], off nt
	global_load_dword v84, v[44:45], off nt
	global_load_dword v85, v[46:47], off nt
	global_load_dword v86, v[48:49], off nt
	global_load_dword v87, v[50:51], off nt
	global_load_dword v88, v[52:53], off nt
	s_add_u32 s12, s12, 0x20000
	s_addc_u32 s13, s13, 0
	v_add_u32_e32 v89, 0x400, v37
	s_waitcnt vmcnt(30)
	ds_write2_b32 v37, v54, v55 offset1:66
	s_waitcnt vmcnt(28)
	ds_write2_b32 v37, v56, v57 offset0:132 offset1:198
	s_waitcnt vmcnt(26)
	ds_write2_b32 v89, v58, v59 offset0:8 offset1:74
	s_waitcnt vmcnt(24)
	ds_write2_b32 v89, v60, v61 offset0:140 offset1:206
	v_add_u32_e32 v37, 0x840, v37
	v_add_u32_e32 v89, 0x400, v37
	s_waitcnt vmcnt(22)
	ds_write2_b32 v37, v65, v66 offset1:66
	s_waitcnt vmcnt(20)
	ds_write2_b32 v37, v67, v68 offset0:132 offset1:198
	s_waitcnt vmcnt(18)
	ds_write2_b32 v89, v69, v70 offset0:8 offset1:74
	s_waitcnt vmcnt(16)
	ds_write2_b32 v89, v71, v72 offset0:140 offset1:206
	v_add_u32_e32 v37, 0x840, v37
	v_add_u32_e32 v89, 0x400, v37
	s_waitcnt vmcnt(14)
	ds_write2_b32 v37, v73, v74 offset1:66
	s_waitcnt vmcnt(12)
	ds_write2_b32 v37, v75, v76 offset0:132 offset1:198
	s_waitcnt vmcnt(10)
	ds_write2_b32 v89, v77, v78 offset0:8 offset1:74
	s_waitcnt vmcnt(8)
	ds_write2_b32 v89, v79, v80 offset0:140 offset1:206
	v_add_u32_e32 v37, 0x840, v37
	v_add_u32_e32 v89, 0x400, v37
	s_waitcnt vmcnt(6)
	ds_write2_b32 v37, v81, v82 offset1:66
	s_waitcnt vmcnt(4)
	ds_write2_b32 v37, v83, v84 offset0:132 offset1:198
	s_waitcnt vmcnt(2)
	ds_write2_b32 v89, v85, v86 offset0:8 offset1:74
	s_waitcnt vmcnt(0)
	ds_write2_b32 v89, v87, v88 offset0:140 offset1:206
	v_add_u32_e32 v37, 0x840, v37
	s_waitcnt lgkmcnt(0)
	ds_read2_b32 v[12:13], v27 offset1:8
	ds_read2_b32 v[16:17], v27 offset0:33 offset1:41
	ds_read2_b32 v[18:19], v27 offset0:66 offset1:74
	ds_read2_b32 v[20:21], v27 offset0:99 offset1:107
	ds_read2_b32 v[22:23], v27 offset0:132 offset1:140
	s_waitcnt lgkmcnt(4)
	v_bfe_u32 v8, v12, 16, 1
	v_add3_u32 v8, v12, v8, s22
	s_waitcnt lgkmcnt(3)
; #define LAS __attribute__((address_space(3)))
; #define LDS_WAIT() asm volatile("s_waitcnt lgkmcnt(0)" ::: "memory")
; __device__ __forceinline__ unsigned pk2(float lo, float hi) { return f2bf(lo) | (f2bf(hi) << 16); }
; __device__ __forceinline__ void transpose_item(const float* W, int K, int N, bf16* WT, int k0, int n0, int drow0, LAS float* scr, int lane) {
;     ...
;     const int c = lane & 7;
; #pragma unroll
;     for (int j = 0; j < 4; ++j) { const int n = (lane >> 3) + 8 * j; const LAS float* s = scr + (8 * c) * 33 + n;
;         v4u o; o.x = pk2(s[0 * 33], s[1 * 33]); o.y = pk2(s[2 * 33], s[3 * 33]); o.z = pk2(s[4 * 33], s[5 * 33]); o.w = pk2(s[6 * 33], s[7 * 33]);
;         __builtin_nontemporal_store(o, (v4u*)(WT + (size_t)(drow0 + n) * K + k0 + 8 * c)); }
;     LDS_WAIT(); asm volatile("" ::: "memory");
; template <bool GU>
; __device__ __forceinline__ void transpose_family(const float* W, int nmat, int K, int N, bf16* WT, size_t dstride, LAS float* scr, int gw, int NGW, int lane) {
;     ...
;     for (int it = gw; it < total; it += NGW) {
;         const int mi = it / per, r = it % per, kb = r / nblk, nb = r % nblk, n0 = nb * 32;
;         int drow0 = n0;
;         if (GU) { const int j = n0 < DFF ? n0 : n0 - DFF; drow0 = (j >> 7) * 256 + (n0 < DFF ? 0 : 128) + (j & 127); }
;         transpose_item(W + (size_t)mi * K * N, K, N, WT + (size_t)mi * dstride, kb * 64, n0, drow0, scr, lane);
	v_bfe_u32 v9, v16, 16, 1
	v_lshrrev_b32_e32 v8, 16, v8
	v_add3_u32 v9, v16, v9, s22
	ds_read2_b32 v[38:39], v27 offset0:165 offset1:173
	v_and_or_b32 v8, v9, s23, v8
	s_waitcnt lgkmcnt(3)
	v_bfe_u32 v9, v18, 16, 1
	v_add3_u32 v9, v18, v9, s22
	s_waitcnt lgkmcnt(2)
	v_bfe_u32 v10, v20, 16, 1
	ds_read2_b32 v[40:41], v27 offset0:198 offset1:206
	v_lshrrev_b32_e32 v9, 16, v9
	v_add3_u32 v10, v20, v10, s22
	ds_read2_b32 v[42:43], v27 offset0:231 offset1:239
	v_and_or_b32 v9, v10, s23, v9
	s_waitcnt lgkmcnt(3)
	v_bfe_u32 v10, v22, 16, 1
	v_add3_u32 v10, v22, v10, s22
	s_waitcnt lgkmcnt(2)
	v_bfe_u32 v11, v38, 16, 1
	v_lshrrev_b32_e32 v10, 16, v10
	v_add3_u32 v11, v38, v11, s22
	s_mul_i32 s12, s27, 0x1600000
	v_and_or_b32 v10, v11, s23, v10
	s_waitcnt lgkmcnt(1)
	v_bfe_u32 v11, v40, 16, 1
	s_mul_hi_i32 s9, s27, 0x1600000
	s_add_u32 s12, s14, s12
	v_add3_u32 v11, v40, v11, s22
	s_waitcnt lgkmcnt(0)
	v_bfe_u32 v12, v42, 16, 1
	s_addc_u32 s9, s15, s9
	s_lshl_b64 s[10:11], s[10:11], 1
	v_lshrrev_b32_e32 v11, 16, v11
	v_add3_u32 v12, v42, v12, s22
	s_add_u32 s10, s12, s10
	v_and_or_b32 v11, v12, s23, v11
	v_or_b32_e32 v12, s8, v24
	s_addc_u32 s11, s9, s11
	v_mul_i32_i24_e32 v44, 0x1600, v12
	v_lshl_add_u64 v[14:15], s[10:11], 0, v[4:5]
	v_ashrrev_i32_e32 v45, 31, v44
	v_lshl_add_u64 v[44:45], v[44:45], 1, v[14:15]
	global_store_dwordx4 v[44:45], v[8:11], off nt
	v_bfe_u32 v12, v43, 16, 1
	v_add3_u32 v12, v43, v12, s22
	v_bfe_u32 v8, v13, 16, 1
	v_add3_u32 v8, v13, v8, s22
	v_bfe_u32 v9, v17, 16, 1
	v_lshrrev_b32_e32 v8, 16, v8
	v_add3_u32 v9, v17, v9, s22
	v_and_or_b32 v8, v9, s23, v8
	v_bfe_u32 v9, v19, 16, 1
	v_add3_u32 v9, v19, v9, s22
	v_bfe_u32 v10, v21, 16, 1
	v_lshrrev_b32_e32 v9, 16, v9
	v_add3_u32 v10, v21, v10, s22
	v_and_or_b32 v9, v10, s23, v9
	v_bfe_u32 v10, v23, 16, 1
	v_add3_u32 v10, v23, v10, s22
	v_bfe_u32 v11, v39, 16, 1
	v_lshrrev_b32_e32 v10, 16, v10
	v_add3_u32 v11, v39, v11, s22
	v_and_or_b32 v10, v11, s23, v10
	v_bfe_u32 v11, v41, 16, 1
	v_add3_u32 v11, v41, v11, s22
	v_lshrrev_b32_e32 v11, 16, v11
	v_and_or_b32 v11, v12, s23, v11
	v_or_b32_e32 v12, s8, v28
	v_mul_i32_i24_e32 v12, 0x1600, v12
	v_ashrrev_i32_e32 v13, 31, v12
	ds_read2_b32 v[16:17], v27 offset0:16 offset1:24
	v_lshl_add_u64 v[12:13], v[12:13], 1, v[14:15]
	global_store_dwordx4 v[12:13], v[8:11], off nt
	ds_read2_b32 v[12:13], v27 offset0:49 offset1:57
	ds_read2_b32 v[18:19], v27 offset0:82 offset1:90
	ds_read2_b32 v[20:21], v27 offset0:115 offset1:123
	s_waitcnt lgkmcnt(3)
	v_bfe_u32 v8, v16, 16, 1
	v_add3_u32 v8, v16, v8, s22
	s_waitcnt lgkmcnt(2)
	v_bfe_u32 v9, v12, 16, 1
	ds_read2_b32 v[22:23], v27 offset0:148 offset1:156
	v_lshrrev_b32_e32 v8, 16, v8
	v_add3_u32 v9, v12, v9, s22
	ds_read2_b32 v[38:39], v27 offset0:181 offset1:189
	v_and_or_b32 v8, v9, s23, v8
	s_waitcnt lgkmcnt(3)
	v_bfe_u32 v9, v18, 16, 1
	v_add3_u32 v9, v18, v9, s22
	s_waitcnt lgkmcnt(2)
	v_bfe_u32 v10, v20, 16, 1
	ds_read2_b32 v[40:41], v27 offset0:214 offset1:222
	v_lshrrev_b32_e32 v9, 16, v9
	v_add3_u32 v10, v20, v10, s22
	ds_read2_b32 v[42:43], v27 offset0:247 offset1:255
	v_and_or_b32 v9, v10, s23, v9
	s_waitcnt lgkmcnt(3)
	v_bfe_u32 v10, v22, 16, 1
	v_add3_u32 v10, v22, v10, s22
	s_waitcnt lgkmcnt(2)
	v_bfe_u32 v11, v38, 16, 1
	v_lshrrev_b32_e32 v10, 16, v10
	v_add3_u32 v11, v38, v11, s22
	v_and_or_b32 v10, v11, s23, v10
	s_waitcnt lgkmcnt(1)
	v_bfe_u32 v11, v40, 16, 1
	v_add3_u32 v11, v40, v11, s22
	s_waitcnt lgkmcnt(0)
	v_bfe_u32 v12, v42, 16, 1
	v_lshrrev_b32_e32 v11, 16, v11
	v_add3_u32 v12, v42, v12, s22
	v_and_or_b32 v11, v12, s23, v11
	v_or_b32_e32 v12, s8, v29
	v_mul_i32_i24_e32 v44, 0x1600, v12
	v_ashrrev_i32_e32 v45, 31, v44
	v_lshl_add_u64 v[44:45], v[44:45], 1, v[14:15]
	global_store_dwordx4 v[44:45], v[8:11], off nt
	v_bfe_u32 v12, v43, 16, 1
	v_add3_u32 v12, v43, v12, s22
	v_bfe_u32 v8, v17, 16, 1
	v_add3_u32 v8, v17, v8, s22
	v_bfe_u32 v9, v13, 16, 1
	v_lshrrev_b32_e32 v8, 16, v8
	v_add3_u32 v9, v13, v9, s22
	v_and_or_b32 v8, v9, s23, v8
	v_bfe_u32 v9, v19, 16, 1
	v_add3_u32 v9, v19, v9, s22
	v_bfe_u32 v10, v21, 16, 1
	v_lshrrev_b32_e32 v9, 16, v9
	v_add3_u32 v10, v21, v10, s22
	v_and_or_b32 v9, v10, s23, v9
	v_bfe_u32 v10, v23, 16, 1
	v_add3_u32 v10, v23, v10, s22
	v_bfe_u32 v11, v39, 16, 1
	v_lshrrev_b32_e32 v10, 16, v10
	v_add3_u32 v11, v39, v11, s22
	v_and_or_b32 v10, v11, s23, v10
	v_bfe_u32 v11, v41, 16, 1
	v_add3_u32 v11, v41, v11, s22
	v_lshrrev_b32_e32 v11, 16, v11
	v_and_or_b32 v11, v12, s23, v11
	v_or_b32_e32 v12, s8, v30
	v_mul_i32_i24_e32 v12, 0x1600, v12
	v_ashrrev_i32_e32 v13, 31, v12
	v_lshl_add_u64 v[12:13], v[12:13], 1, v[14:15]
	global_store_dwordx4 v[12:13], v[8:11], off nt
	s_waitcnt lgkmcnt(0)
	s_add_i32 s26, s26, s62
	s_cmpk_lt_i32 s26, 0x5800
	s_cbranch_scc1 .LBB0_34
